# hand-written in-proj epilogue for the gate/conv column tiles (batched row-statistics reduction, packed f32 math) + PB conversion of layers 1-3 deferred into the barrier wait after in-proj
# speedup vs baseline: 1.0091x; 1.0091x over previous
; __device__ __forceinline__ float* ka_out() { return (float*)(GAS float*)ka_u64(120); }
; __device__ __forceinline__ unsigned char* ka_ws() { return (unsigned char*)(GAS unsigned char*)ka_u64(128); }
;     __device__ __forceinline__ void operator()(const f32x4 (&acc)[2][2][4][2], const pg8::Unit& u, int wr, int wc, int fr_, int fq_) const {
;         int lane_ = fr_ + 16 * fq_; asm volatile("" : "+v"(lane_)); const int fr = lane_ & 15, fq = lane_ >> 4;
;         const int pn = u.pn; unsigned char* ws = ka_ws(); float* out = ka_out();
;         const float* ssp = (const float*)(ws + WS_SSP); const float* tab = (const float*)(ws + WS_TAB);
;         bf16_t *Q = (bf16_t*)(ws + WS_Q), *K = (bf16_t*)(ws + WS_K), *V = (bf16_t*)(ws + WS_V), *SGA = (bf16_t*)(ws + WS_SGA), *BGC = (bf16_t*)(ws + WS_BGC), *U = (bf16_t*)(ws + WS_U);
;         const bool rope = pn < 2 || (pn == 2 && wc < 2);
;         const int row0 = u.pm * 256 + wr * 64 + fr, cw = wc * 32 + fq * 8;
;         Ld ld[8];
; #pragma unroll
;         for (int it = 0; it < 10; ++it) {
;             if (it < 8) {
;                 const int row = row0 + (it >> 2) * 128 + (it & 3) * 16;
;                 ld[it].ss = gld<f32x4>(ssp + (size_t)row * 16 + fq * 4);
;                 if (rope) { const int pidx = row < NPR ? (row & 2047) : 2048 + (row & 3); const float* tp = tab + (size_t)pidx * 64 + fq * 8;
;                     ld[it].c0 = gld<f32x4>(tp); ld[it].c1 = gld<f32x4>(tp + 4); ld[it].s0 = gld<f32x4>(tp + 32); ld[it].s1 = gld<f32x4>(tp + 36); }
.LBB0_280:
	s_cmp_gt_i32 s6, 2
	s_cbranch_scc1 .Lme_entry
	s_cmp_gt_i32 s6, 1
	v_mov_b32_e32 v190, v248
	s_mov_b64 s[8:9], s[0:1]
	s_cselect_b64 s[16:17], -1, 0
	s_cmp_lt_i32 s6, 2
	s_cselect_b64 s[18:19], -1, 0
	s_cmp_lg_u32 s6, 2
	s_load_dwordx2 s[10:11], s[8:9], 0x80
	s_cselect_b64 s[8:9], -1, 0
	s_cmp_eq_u32 s6, 2
	s_cselect_b64 s[30:31], -1, 0
	s_lshl_b32 s71, s4, 8
	v_ashrrev_i32_e32 v98, 4, v190
	s_add_i32 s71, s71, s89
	v_and_or_b32 v210, v190, 15, s71
	v_lshlrev_b32_e32 v96, 2, v98
	v_ashrrev_i32_e32 v97, 31, v96
	v_ashrrev_i32_e32 v211, 31, v210
	s_waitcnt lgkmcnt(0)
	v_lshl_add_u64 v[236:237], v[96:97], 2, s[10:11]
	v_lshlrev_b64 v[96:97], 6, v[210:211]
	s_mov_b64 s[12:13], s[0:1]
	v_lshl_add_u64 v[96:97], v[236:237], 0, v[96:97]
	global_load_dwordx4 v[184:187], v[96:97], off
	s_load_dwordx2 s[28:29], s[12:13], 0x78
	s_and_b64 s[4:5], s[30:31], s[66:67]
	v_lshlrev_b32_e32 v188, 3, v98
	s_or_b64 s[4:5], s[18:19], s[4:5]
	v_ashrrev_i32_e32 v189, 31, v188
	s_xor_b64 s[84:85], s[4:5], -1
	v_and_b32_e32 v191, 3, v190
	v_lshl_add_u64 v[96:97], v[188:189], 2, s[10:11]
	s_mov_b64 s[12:13], 0xfd00000
	v_or_b32_e32 v252, 0x800, v191
	v_lshl_add_u64 v[234:235], v[96:97], 0, s[12:13]
	s_and_b64 vcc, exec, s[84:85]
	s_cbranch_vccnz .LBB0_282
	v_and_b32_e32 v96, 0x7cf, v210
	v_cmp_gt_i32_e32 vcc, s44, v210
	s_nop 1
	v_cndmask_b32_e32 v96, v252, v96, vcc
	v_lshlrev_b32_e32 v192, 8, v96
	v_lshl_add_u64 v[96:97], v[234:235], 0, v[192:193]
	global_load_dwordx4 v[152:155], v[96:97], off offset:16
	global_load_dwordx4 v[176:179], v[96:97], off
	global_load_dwordx4 v[172:175], v[96:97], off offset:144
	global_load_dwordx4 v[180:183], v[96:97], off offset:128

; __device__ __forceinline__ u32x4 pk8(f32x4 a, f32x4 b) { u32x4 w; w.x = pk2(a[0], a[1]); w.y = pk2(a[2], a[3]); w.z = pk2(b[0], b[1]); w.w = pk2(b[2], b[3]); return w; }
; __device__ __forceinline__ f32x4 silu4(f32x4 x) { f32x4 r; for (int i = 0; i < 4; ++i) r[i] = x[i] * sigm(x[i]); return r; }
;     __device__ __forceinline__ void operator()(const f32x4 (&acc)[2][2][4][2], const pg8::Unit& u, int wr, int wc, int fr_, int fq_) const {
;     ...
;                 const int row = row0 + (it >> 2) * 128 + (it & 3) * 16;
;                 ld[it].ss = gld<f32x4>(ssp + (size_t)row * 16 + fq * 4);
;                 if (rope) { const int pidx = row < NPR ? (row & 2047) : 2048 + (row & 3); const float* tp = tab + (size_t)pidx * 64 + fq * 8;
;                     ld[it].c0 = gld<f32x4>(tp); ld[it].c1 = gld<f32x4>(tp + 4); ld[it].s0 = gld<f32x4>(tp + 32); ld[it].s1 = gld<f32x4>(tp + 36); }
;             }
;             if (it >= 2) {
;                 const int k = it - 2, ai = k >> 2, m = k & 3, row = row0 + ai * 128 + m * 16;
;                 float sq = (ld[k].ss[0] + ld[k].ss[1]) + (ld[k].ss[2] + ld[k].ss[3]); sq += __shfl_xor(sq, 16); sq += __shfl_xor(sq, 32);
;                 const float rs = __builtin_amdgcn_rsqf(sq * (1.f / 1024.f) + EPS);
;     ...
;                 } else if (pn < 5) {
;                     bf16_t* p = SGA + (size_t)row * 512 + (pn - 3) * 256 + cw;
;                     gst<u32x4>(p, pk8(silu4(a0), silu4(a1))); gst<u32x4>(p + 128, pk8(silu4(b0), silu4(b1)));
.Lme_entry:
	s_load_dwordx2 s[10:11], s[0:1], 0x80
	s_load_dwordx2 s[28:29], s[0:1], 0x78
	v_readlane_b32 s20, v255, 36
	s_lshl_b32 s71, s4, 8
	s_add_i32 s71, s71, s89
	v_and_or_b32 v210, v248, 15, s71
	v_lshrrev_b32_e32 v211, 4, v248
	v_lshlrev_b32_e32 v212, 6, v210
	v_lshl_add_u32 v212, v211, 4, v212
	v_add_u32_e32 v213, 0x2000, v212
	v_xor_b32_e32 v250, 16, v248
	v_lshlrev_b32_e32 v250, 2, v250
	v_xor_b32_e32 v251, 32, v248
	v_lshlrev_b32_e32 v251, 2, v251
	v_lshlrev_b32_e32 v214, 10, v210
	v_lshl_add_u32 v214, v211, 4, v214
	s_waitcnt lgkmcnt(0)
	global_load_dwordx4 v[144:147], v212, s[10:11]
	global_load_dwordx4 v[148:151], v212, s[10:11] offset:1024
	global_load_dwordx4 v[152:155], v212, s[10:11] offset:2048
	global_load_dwordx4 v[156:159], v212, s[10:11] offset:3072
	global_load_dwordx4 v[160:163], v213, s[10:11]
	global_load_dwordx4 v[164:167], v213, s[10:11] offset:1024
	global_load_dwordx4 v[168:171], v213, s[10:11] offset:2048
	global_load_dwordx4 v[172:175], v213, s[10:11] offset:3072
	s_cmp_gt_i32 s6, 8
	s_cbranch_scc1 .Lme_ubase
	s_cmp_gt_i32 s6, 4
	s_cbranch_scc1 .Lme_bbase
	s_add_i32 s12, s6, -3
	s_lshl_b32 s12, s12, 9
	s_add_i32 s12, s12, s93
	s_add_u32 s12, s12, 0xc280000
	s_branch .Lme_base_done
.Lme_bbase:
	s_add_i32 s12, s6, -5
	s_lshl_b32 s12, s12, 8
	s_add_i32 s12, s12, s93
	s_add_u32 s12, s12, 0xd300000
	s_branch .Lme_base_done
.Lme_ubase:
	s_add_i32 s12, s6, -9
	s_lshl_b32 s12, s12, 8
	s_add_i32 s12, s12, s93
	s_add_u32 s12, s12, 0xe380000
.Lme_base_done:
	s_add_u32 s16, s10, s12
	s_addc_u32 s17, s11, 0
	s_mov_b32 s30, 0xbfb8aa3b
	s_mov_b32 s31, s30
	s_waitcnt vmcnt(0)
	v_add_f32_e32 v144, v144, v145
	v_add_f32_e32 v146, v146, v147
	v_add_f32_e32 v148, v148, v149
	v_add_f32_e32 v150, v150, v151
	v_add_f32_e32 v152, v152, v153
	v_add_f32_e32 v154, v154, v155
	v_add_f32_e32 v156, v156, v157
	v_add_f32_e32 v158, v158, v159
	v_add_f32_e32 v160, v160, v161
	v_add_f32_e32 v162, v162, v163
	v_add_f32_e32 v164, v164, v165
	v_add_f32_e32 v166, v166, v167
	v_add_f32_e32 v168, v168, v169
	v_add_f32_e32 v170, v170, v171
	v_add_f32_e32 v172, v172, v173
	v_add_f32_e32 v174, v174, v175
	v_add_f32_e32 v144, v144, v146
	v_add_f32_e32 v148, v148, v150
	v_add_f32_e32 v152, v152, v154
	v_add_f32_e32 v156, v156, v158
	v_add_f32_e32 v160, v160, v162
	v_add_f32_e32 v164, v164, v166
	v_add_f32_e32 v168, v168, v170
	v_add_f32_e32 v172, v172, v174
	ds_bpermute_b32 v145, v250, v144
	ds_bpermute_b32 v149, v250, v148
	ds_bpermute_b32 v153, v250, v152
	ds_bpermute_b32 v157, v250, v156
	ds_bpermute_b32 v161, v250, v160
	ds_bpermute_b32 v165, v250, v164
	ds_bpermute_b32 v169, v250, v168
	ds_bpermute_b32 v173, v250, v172
	s_waitcnt lgkmcnt(0)
	v_add_f32_e32 v144, v144, v145
	v_add_f32_e32 v148, v148, v149
	v_add_f32_e32 v152, v152, v153
	v_add_f32_e32 v156, v156, v157
	v_add_f32_e32 v160, v160, v161
	v_add_f32_e32 v164, v164, v165
	v_add_f32_e32 v168, v168, v169
	v_add_f32_e32 v172, v172, v173
	ds_bpermute_b32 v145, v251, v144
	ds_bpermute_b32 v149, v251, v148
	ds_bpermute_b32 v153, v251, v152
	ds_bpermute_b32 v157, v251, v156
	ds_bpermute_b32 v161, v251, v160
	ds_bpermute_b32 v165, v251, v164
	ds_bpermute_b32 v169, v251, v168
	ds_bpermute_b32 v173, v251, v172
	s_waitcnt lgkmcnt(0)
	v_add_f32_e32 v144, v144, v145
	v_add_f32_e32 v148, v148, v149
	v_add_f32_e32 v152, v152, v153
	v_add_f32_e32 v156, v156, v157
	v_add_f32_e32 v160, v160, v161
	v_add_f32_e32 v164, v164, v165
	v_add_f32_e32 v168, v168, v169
	v_add_f32_e32 v172, v172, v173
	v_fmamk_f32 v144, v144, 0x3a800000, v243
	v_fmamk_f32 v148, v148, 0x3a800000, v243
	v_fmamk_f32 v152, v152, 0x3a800000, v243
	v_fmamk_f32 v156, v156, 0x3a800000, v243
	v_fmamk_f32 v160, v160, 0x3a800000, v243
	v_fmamk_f32 v164, v164, 0x3a800000, v243
	v_fmamk_f32 v168, v168, 0x3a800000, v243
	v_fmamk_f32 v172, v172, 0x3a800000, v243
	v_rsq_f32_e32 v176, v144
	v_rsq_f32_e32 v178, v148
	v_rsq_f32_e32 v180, v152
	v_rsq_f32_e32 v182, v156
	v_rsq_f32_e32 v184, v160
	v_rsq_f32_e32 v186, v164
	v_rsq_f32_e32 v188, v168
	v_rsq_f32_e32 v190, v172
	s_cmp_gt_i32 s6, 8
	s_cbranch_scc1 .Lme_upath
	s_cmp_gt_i32 s6, 4
	s_cbranch_scc1 .Lme_bpath
	v_pk_mul_f32 v[132:133], v[132:133], v[176:177] op_sel_hi:[1,0]
	v_pk_mul_f32 v[134:135], v[134:135], v[176:177] op_sel_hi:[1,0]
	v_pk_mul_f32 v[128:129], v[128:129], v[176:177] op_sel_hi:[1,0]
	v_pk_mul_f32 v[130:131], v[130:131], v[176:177] op_sel_hi:[1,0]
	v_pk_mul_f32 v[116:117], v[116:117], v[176:177] op_sel_hi:[1,0]
	v_pk_mul_f32 v[118:119], v[118:119], v[176:177] op_sel_hi:[1,0]
	v_pk_mul_f32 v[112:113], v[112:113], v[176:177] op_sel_hi:[1,0]
	v_pk_mul_f32 v[114:115], v[114:115], v[176:177] op_sel_hi:[1,0]
	v_pk_mul_f32 v[96:97], v[132:133], s[30:31]
	v_pk_mul_f32 v[98:99], v[134:135], s[30:31]
	v_pk_mul_f32 v[100:101], v[128:129], s[30:31]
	v_pk_mul_f32 v[102:103], v[130:131], s[30:31]
	v_exp_f32_e32 v96, v96
	v_exp_f32_e32 v97, v97
	v_exp_f32_e32 v98, v98
	v_exp_f32_e32 v99, v99
	v_exp_f32_e32 v100, v100
	v_exp_f32_e32 v101, v101
	v_exp_f32_e32 v102, v102
	v_exp_f32_e32 v103, v103
	v_pk_add_f32 v[96:97], v[96:97], 1.0 op_sel_hi:[1,0]
	v_pk_add_f32 v[98:99], v[98:99], 1.0 op_sel_hi:[1,0]
	v_pk_add_f32 v[100:101], v[100:101], 1.0 op_sel_hi:[1,0]
	v_pk_add_f32 v[102:103], v[102:103], 1.0 op_sel_hi:[1,0]
	v_rcp_f32_e32 v96, v96
	v_rcp_f32_e32 v97, v97
	v_rcp_f32_e32 v98, v98
	v_rcp_f32_e32 v99, v99
	v_rcp_f32_e32 v100, v100
	v_rcp_f32_e32 v101, v101
	v_rcp_f32_e32 v102, v102
	v_rcp_f32_e32 v103, v103
	v_pk_mul_f32 v[132:133], v[132:133], v[96:97]
	v_pk_mul_f32 v[134:135], v[134:135], v[98:99]
	v_pk_mul_f32 v[128:129], v[128:129], v[100:101]
	v_pk_mul_f32 v[130:131], v[130:131], v[102:103]
; __device__ __forceinline__ u32x4 pk8(f32x4 a, f32x4 b) { u32x4 w; w.x = pk2(a[0], a[1]); w.y = pk2(a[2], a[3]); w.z = pk2(b[0], b[1]); w.w = pk2(b[2], b[3]); return w; }
; __device__ __forceinline__ f32x4 silu4(f32x4 x) { f32x4 r; for (int i = 0; i < 4; ++i) r[i] = x[i] * sigm(x[i]); return r; }
; __device__ __forceinline__ float sigm(float x) { return __builtin_amdgcn_rcpf(1.f + __builtin_amdgcn_exp2f(-x * LOG2E)); }
;     __device__ __forceinline__ void operator()(const f32x4 (&acc)[2][2][4][2], const pg8::Unit& u, int wr, int wc, int fr_, int fq_) const {
;     ...
;                 } else if (pn < 5) {
;                     bf16_t* p = SGA + (size_t)row * 512 + (pn - 3) * 256 + cw;
;                     gst<u32x4>(p, pk8(silu4(a0), silu4(a1))); gst<u32x4>(p + 128, pk8(silu4(b0), silu4(b1)));
	v_pk_mul_f32 v[96:97], v[116:117], s[30:31]
	v_pk_mul_f32 v[98:99], v[118:119], s[30:31]
	v_pk_mul_f32 v[100:101], v[112:113], s[30:31]
	v_pk_mul_f32 v[102:103], v[114:115], s[30:31]
	v_exp_f32_e32 v96, v96
	v_exp_f32_e32 v97, v97
	v_exp_f32_e32 v98, v98
	v_exp_f32_e32 v99, v99
	v_exp_f32_e32 v100, v100
	v_exp_f32_e32 v101, v101
	v_exp_f32_e32 v102, v102
	v_exp_f32_e32 v103, v103
	v_pk_add_f32 v[96:97], v[96:97], 1.0 op_sel_hi:[1,0]
	v_pk_add_f32 v[98:99], v[98:99], 1.0 op_sel_hi:[1,0]
	v_pk_add_f32 v[100:101], v[100:101], 1.0 op_sel_hi:[1,0]
	v_pk_add_f32 v[102:103], v[102:103], 1.0 op_sel_hi:[1,0]
	v_rcp_f32_e32 v96, v96
	v_rcp_f32_e32 v97, v97
	v_rcp_f32_e32 v98, v98
	v_rcp_f32_e32 v99, v99
	v_rcp_f32_e32 v100, v100
	v_rcp_f32_e32 v101, v101
	v_rcp_f32_e32 v102, v102
	v_rcp_f32_e32 v103, v103
	v_pk_mul_f32 v[116:117], v[116:117], v[96:97]
	v_pk_mul_f32 v[118:119], v[118:119], v[98:99]
	v_pk_mul_f32 v[112:113], v[112:113], v[100:101]
	v_pk_mul_f32 v[114:115], v[114:115], v[102:103]
	v_cvt_pk_bf16_f32 v104, v132, v133
	v_cvt_pk_bf16_f32 v105, v134, v135
	v_cvt_pk_bf16_f32 v106, v128, v129
	v_cvt_pk_bf16_f32 v107, v130, v131
	global_store_dwordx4 v214, v[104:107], s[16:17]
	v_cvt_pk_bf16_f32 v218, v116, v117
	v_cvt_pk_bf16_f32 v219, v118, v119
	v_cvt_pk_bf16_f32 v220, v112, v113
	v_cvt_pk_bf16_f32 v221, v114, v115
	global_store_dwordx4 v214, v[218:221], s[16:17] offset:256
	s_add_u32 s16, s16, 0x4000
	s_addc_u32 s17, s17, 0
	v_pk_mul_f32 v[140:141], v[140:141], v[178:179] op_sel_hi:[1,0]
	v_pk_mul_f32 v[142:143], v[142:143], v[178:179] op_sel_hi:[1,0]
	v_pk_mul_f32 v[136:137], v[136:137], v[178:179] op_sel_hi:[1,0]
	v_pk_mul_f32 v[138:139], v[138:139], v[178:179] op_sel_hi:[1,0]
	v_pk_mul_f32 v[124:125], v[124:125], v[178:179] op_sel_hi:[1,0]
	v_pk_mul_f32 v[126:127], v[126:127], v[178:179] op_sel_hi:[1,0]
	v_pk_mul_f32 v[120:121], v[120:121], v[178:179] op_sel_hi:[1,0]
	v_pk_mul_f32 v[122:123], v[122:123], v[178:179] op_sel_hi:[1,0]
	v_pk_mul_f32 v[96:97], v[140:141], s[30:31]
	v_pk_mul_f32 v[98:99], v[142:143], s[30:31]
	v_pk_mul_f32 v[100:101], v[136:137], s[30:31]
	v_pk_mul_f32 v[102:103], v[138:139], s[30:31]
	v_exp_f32_e32 v96, v96
	v_exp_f32_e32 v97, v97
	v_exp_f32_e32 v98, v98
	v_exp_f32_e32 v99, v99
	v_exp_f32_e32 v100, v100
	v_exp_f32_e32 v101, v101
	v_exp_f32_e32 v102, v102
	v_exp_f32_e32 v103, v103
	v_pk_add_f32 v[96:97], v[96:97], 1.0 op_sel_hi:[1,0]
	v_pk_add_f32 v[98:99], v[98:99], 1.0 op_sel_hi:[1,0]
	v_pk_add_f32 v[100:101], v[100:101], 1.0 op_sel_hi:[1,0]
	v_pk_add_f32 v[102:103], v[102:103], 1.0 op_sel_hi:[1,0]
	v_rcp_f32_e32 v96, v96
	v_rcp_f32_e32 v97, v97
	v_rcp_f32_e32 v98, v98
	v_rcp_f32_e32 v99, v99
	v_rcp_f32_e32 v100, v100
	v_rcp_f32_e32 v101, v101
	v_rcp_f32_e32 v102, v102
	v_rcp_f32_e32 v103, v103
	v_pk_mul_f32 v[140:141], v[140:141], v[96:97]
	v_pk_mul_f32 v[142:143], v[142:143], v[98:99]
	v_pk_mul_f32 v[136:137], v[136:137], v[100:101]
	v_pk_mul_f32 v[138:139], v[138:139], v[102:103]
	v_pk_mul_f32 v[96:97], v[124:125], s[30:31]
	v_pk_mul_f32 v[98:99], v[126:127], s[30:31]
	v_pk_mul_f32 v[100:101], v[120:121], s[30:31]
	v_pk_mul_f32 v[102:103], v[122:123], s[30:31]
	v_exp_f32_e32 v96, v96
	v_exp_f32_e32 v97, v97
	v_exp_f32_e32 v98, v98
	v_exp_f32_e32 v99, v99
	v_exp_f32_e32 v100, v100
	v_exp_f32_e32 v101, v101
	v_exp_f32_e32 v102, v102
	v_exp_f32_e32 v103, v103
	v_pk_add_f32 v[96:97], v[96:97], 1.0 op_sel_hi:[1,0]
	v_pk_add_f32 v[98:99], v[98:99], 1.0 op_sel_hi:[1,0]
	v_pk_add_f32 v[100:101], v[100:101], 1.0 op_sel_hi:[1,0]
	v_pk_add_f32 v[102:103], v[102:103], 1.0 op_sel_hi:[1,0]
	v_rcp_f32_e32 v96, v96
	v_rcp_f32_e32 v97, v97
	v_rcp_f32_e32 v98, v98
	v_rcp_f32_e32 v99, v99
	v_rcp_f32_e32 v100, v100
	v_rcp_f32_e32 v101, v101
	v_rcp_f32_e32 v102, v102
	v_rcp_f32_e32 v103, v103
	v_pk_mul_f32 v[124:125], v[124:125], v[96:97]
	v_pk_mul_f32 v[126:127], v[126:127], v[98:99]
	v_pk_mul_f32 v[120:121], v[120:121], v[100:101]
	v_pk_mul_f32 v[122:123], v[122:123], v[102:103]
	v_cvt_pk_bf16_f32 v108, v140, v141
	v_cvt_pk_bf16_f32 v109, v142, v143
	v_cvt_pk_bf16_f32 v110, v136, v137
	v_cvt_pk_bf16_f32 v111, v138, v139
	global_store_dwordx4 v214, v[108:111], s[16:17]
	v_cvt_pk_bf16_f32 v222, v124, v125
	v_cvt_pk_bf16_f32 v223, v126, v127
	v_cvt_pk_bf16_f32 v224, v120, v121
	v_cvt_pk_bf16_f32 v225, v122, v123
	global_store_dwordx4 v214, v[222:225], s[16:17] offset:256
	s_add_u32 s16, s16, 0x4000
	s_addc_u32 s17, s17, 0
	v_pk_mul_f32 v[92:93], v[92:93], v[180:181] op_sel_hi:[1,0]
	v_pk_mul_f32 v[94:95], v[94:95], v[180:181] op_sel_hi:[1,0]
	v_pk_mul_f32 v[88:89], v[88:89], v[180:181] op_sel_hi:[1,0]
	v_pk_mul_f32 v[90:91], v[90:91], v[180:181] op_sel_hi:[1,0]
	v_pk_mul_f32 v[84:85], v[84:85], v[180:181] op_sel_hi:[1,0]
	v_pk_mul_f32 v[86:87], v[86:87], v[180:181] op_sel_hi:[1,0]
	v_pk_mul_f32 v[80:81], v[80:81], v[180:181] op_sel_hi:[1,0]
	v_pk_mul_f32 v[82:83], v[82:83], v[180:181] op_sel_hi:[1,0]
	v_pk_mul_f32 v[96:97], v[92:93], s[30:31]
	v_pk_mul_f32 v[98:99], v[94:95], s[30:31]
	v_pk_mul_f32 v[100:101], v[88:89], s[30:31]
	v_pk_mul_f32 v[102:103], v[90:91], s[30:31]
	v_exp_f32_e32 v96, v96
	v_exp_f32_e32 v97, v97
	v_exp_f32_e32 v98, v98
	v_exp_f32_e32 v99, v99
	v_exp_f32_e32 v100, v100
	v_exp_f32_e32 v101, v101
	v_exp_f32_e32 v102, v102
	v_exp_f32_e32 v103, v103
	v_pk_add_f32 v[96:97], v[96:97], 1.0 op_sel_hi:[1,0]
	v_pk_add_f32 v[98:99], v[98:99], 1.0 op_sel_hi:[1,0]
	v_pk_add_f32 v[100:101], v[100:101], 1.0 op_sel_hi:[1,0]
	v_pk_add_f32 v[102:103], v[102:103], 1.0 op_sel_hi:[1,0]
	v_rcp_f32_e32 v96, v96
	v_rcp_f32_e32 v97, v97
	v_rcp_f32_e32 v98, v98
	v_rcp_f32_e32 v99, v99
	v_rcp_f32_e32 v100, v100
; __device__ __forceinline__ u32x4 pk8(f32x4 a, f32x4 b) { u32x4 w; w.x = pk2(a[0], a[1]); w.y = pk2(a[2], a[3]); w.z = pk2(b[0], b[1]); w.w = pk2(b[2], b[3]); return w; }
; __device__ __forceinline__ f32x4 silu4(f32x4 x) { f32x4 r; for (int i = 0; i < 4; ++i) r[i] = x[i] * sigm(x[i]); return r; }
; __device__ __forceinline__ float sigm(float x) { return __builtin_amdgcn_rcpf(1.f + __builtin_amdgcn_exp2f(-x * LOG2E)); }
;     __device__ __forceinline__ void operator()(const f32x4 (&acc)[2][2][4][2], const pg8::Unit& u, int wr, int wc, int fr_, int fq_) const {
;     ...
;                 } else if (pn < 5) {
;                     bf16_t* p = SGA + (size_t)row * 512 + (pn - 3) * 256 + cw;
;                     gst<u32x4>(p, pk8(silu4(a0), silu4(a1))); gst<u32x4>(p + 128, pk8(silu4(b0), silu4(b1)));
	v_rcp_f32_e32 v101, v101
	v_rcp_f32_e32 v102, v102
	v_rcp_f32_e32 v103, v103
	v_pk_mul_f32 v[92:93], v[92:93], v[96:97]
	v_pk_mul_f32 v[94:95], v[94:95], v[98:99]
	v_pk_mul_f32 v[88:89], v[88:89], v[100:101]
	v_pk_mul_f32 v[90:91], v[90:91], v[102:103]
	v_pk_mul_f32 v[96:97], v[84:85], s[30:31]
	v_pk_mul_f32 v[98:99], v[86:87], s[30:31]
	v_pk_mul_f32 v[100:101], v[80:81], s[30:31]
	v_pk_mul_f32 v[102:103], v[82:83], s[30:31]
	v_exp_f32_e32 v96, v96
	v_exp_f32_e32 v97, v97
	v_exp_f32_e32 v98, v98
	v_exp_f32_e32 v99, v99
	v_exp_f32_e32 v100, v100
	v_exp_f32_e32 v101, v101
	v_exp_f32_e32 v102, v102
	v_exp_f32_e32 v103, v103
	v_pk_add_f32 v[96:97], v[96:97], 1.0 op_sel_hi:[1,0]
	v_pk_add_f32 v[98:99], v[98:99], 1.0 op_sel_hi:[1,0]
	v_pk_add_f32 v[100:101], v[100:101], 1.0 op_sel_hi:[1,0]
	v_pk_add_f32 v[102:103], v[102:103], 1.0 op_sel_hi:[1,0]
	v_rcp_f32_e32 v96, v96
	v_rcp_f32_e32 v97, v97
	v_rcp_f32_e32 v98, v98
	v_rcp_f32_e32 v99, v99
	v_rcp_f32_e32 v100, v100
	v_rcp_f32_e32 v101, v101
	v_rcp_f32_e32 v102, v102
	v_rcp_f32_e32 v103, v103
	v_pk_mul_f32 v[84:85], v[84:85], v[96:97]
	v_pk_mul_f32 v[86:87], v[86:87], v[98:99]
	v_pk_mul_f32 v[80:81], v[80:81], v[100:101]
	v_pk_mul_f32 v[82:83], v[82:83], v[102:103]
	v_cvt_pk_bf16_f32 v104, v92, v93
	v_cvt_pk_bf16_f32 v105, v94, v95
	v_cvt_pk_bf16_f32 v106, v88, v89
	v_cvt_pk_bf16_f32 v107, v90, v91
	global_store_dwordx4 v214, v[104:107], s[16:17]
	v_cvt_pk_bf16_f32 v218, v84, v85
	v_cvt_pk_bf16_f32 v219, v86, v87
	v_cvt_pk_bf16_f32 v220, v80, v81
	v_cvt_pk_bf16_f32 v221, v82, v83
	global_store_dwordx4 v214, v[218:221], s[16:17] offset:256
	s_add_u32 s16, s16, 0x4000
	s_addc_u32 s17, s17, 0
	v_pk_mul_f32 v[76:77], v[76:77], v[182:183] op_sel_hi:[1,0]
	v_pk_mul_f32 v[78:79], v[78:79], v[182:183] op_sel_hi:[1,0]
	v_pk_mul_f32 v[72:73], v[72:73], v[182:183] op_sel_hi:[1,0]
	v_pk_mul_f32 v[74:75], v[74:75], v[182:183] op_sel_hi:[1,0]
	v_pk_mul_f32 v[68:69], v[68:69], v[182:183] op_sel_hi:[1,0]
	v_pk_mul_f32 v[70:71], v[70:71], v[182:183] op_sel_hi:[1,0]
	v_pk_mul_f32 v[64:65], v[64:65], v[182:183] op_sel_hi:[1,0]
	v_pk_mul_f32 v[66:67], v[66:67], v[182:183] op_sel_hi:[1,0]
	v_pk_mul_f32 v[96:97], v[76:77], s[30:31]
	v_pk_mul_f32 v[98:99], v[78:79], s[30:31]
	v_pk_mul_f32 v[100:101], v[72:73], s[30:31]
	v_pk_mul_f32 v[102:103], v[74:75], s[30:31]
	v_exp_f32_e32 v96, v96
	v_exp_f32_e32 v97, v97
	v_exp_f32_e32 v98, v98
	v_exp_f32_e32 v99, v99
	v_exp_f32_e32 v100, v100
	v_exp_f32_e32 v101, v101
	v_exp_f32_e32 v102, v102
	v_exp_f32_e32 v103, v103
	v_pk_add_f32 v[96:97], v[96:97], 1.0 op_sel_hi:[1,0]
	v_pk_add_f32 v[98:99], v[98:99], 1.0 op_sel_hi:[1,0]
	v_pk_add_f32 v[100:101], v[100:101], 1.0 op_sel_hi:[1,0]
	v_pk_add_f32 v[102:103], v[102:103], 1.0 op_sel_hi:[1,0]
	v_rcp_f32_e32 v96, v96
	v_rcp_f32_e32 v97, v97
	v_rcp_f32_e32 v98, v98
	v_rcp_f32_e32 v99, v99
	v_rcp_f32_e32 v100, v100
	v_rcp_f32_e32 v101, v101
	v_rcp_f32_e32 v102, v102
	v_rcp_f32_e32 v103, v103
	v_pk_mul_f32 v[76:77], v[76:77], v[96:97]
	v_pk_mul_f32 v[78:79], v[78:79], v[98:99]
	v_pk_mul_f32 v[72:73], v[72:73], v[100:101]
	v_pk_mul_f32 v[74:75], v[74:75], v[102:103]
	v_pk_mul_f32 v[96:97], v[68:69], s[30:31]
	v_pk_mul_f32 v[98:99], v[70:71], s[30:31]
	v_pk_mul_f32 v[100:101], v[64:65], s[30:31]
	v_pk_mul_f32 v[102:103], v[66:67], s[30:31]
	v_exp_f32_e32 v96, v96
	v_exp_f32_e32 v97, v97
	v_exp_f32_e32 v98, v98
	v_exp_f32_e32 v99, v99
	v_exp_f32_e32 v100, v100
	v_exp_f32_e32 v101, v101
	v_exp_f32_e32 v102, v102
	v_exp_f32_e32 v103, v103
	v_pk_add_f32 v[96:97], v[96:97], 1.0 op_sel_hi:[1,0]
	v_pk_add_f32 v[98:99], v[98:99], 1.0 op_sel_hi:[1,0]
	v_pk_add_f32 v[100:101], v[100:101], 1.0 op_sel_hi:[1,0]
	v_pk_add_f32 v[102:103], v[102:103], 1.0 op_sel_hi:[1,0]
	v_rcp_f32_e32 v96, v96
	v_rcp_f32_e32 v97, v97
	v_rcp_f32_e32 v98, v98
	v_rcp_f32_e32 v99, v99
	v_rcp_f32_e32 v100, v100
	v_rcp_f32_e32 v101, v101
	v_rcp_f32_e32 v102, v102
	v_rcp_f32_e32 v103, v103
	v_pk_mul_f32 v[68:69], v[68:69], v[96:97]
	v_pk_mul_f32 v[70:71], v[70:71], v[98:99]
	v_pk_mul_f32 v[64:65], v[64:65], v[100:101]
	v_pk_mul_f32 v[66:67], v[66:67], v[102:103]
	v_cvt_pk_bf16_f32 v108, v76, v77
	v_cvt_pk_bf16_f32 v109, v78, v79
	v_cvt_pk_bf16_f32 v110, v72, v73
	v_cvt_pk_bf16_f32 v111, v74, v75
	global_store_dwordx4 v214, v[108:111], s[16:17]
	v_cvt_pk_bf16_f32 v222, v68, v69
	v_cvt_pk_bf16_f32 v223, v70, v71
	v_cvt_pk_bf16_f32 v224, v64, v65
	v_cvt_pk_bf16_f32 v225, v66, v67
	global_store_dwordx4 v214, v[222:225], s[16:17] offset:256
	s_add_u32 s16, s16, 0x14000
	s_addc_u32 s17, s17, 0
	v_pk_mul_f32 v[60:61], v[60:61], v[184:185] op_sel_hi:[1,0]
	v_pk_mul_f32 v[62:63], v[62:63], v[184:185] op_sel_hi:[1,0]
	v_pk_mul_f32 v[56:57], v[56:57], v[184:185] op_sel_hi:[1,0]
	v_pk_mul_f32 v[58:59], v[58:59], v[184:185] op_sel_hi:[1,0]
	v_pk_mul_f32 v[52:53], v[52:53], v[184:185] op_sel_hi:[1,0]
	v_pk_mul_f32 v[54:55], v[54:55], v[184:185] op_sel_hi:[1,0]
	v_pk_mul_f32 v[48:49], v[48:49], v[184:185] op_sel_hi:[1,0]
	v_pk_mul_f32 v[50:51], v[50:51], v[184:185] op_sel_hi:[1,0]
	v_pk_mul_f32 v[96:97], v[60:61], s[30:31]
	v_pk_mul_f32 v[98:99], v[62:63], s[30:31]
	v_pk_mul_f32 v[100:101], v[56:57], s[30:31]
	v_pk_mul_f32 v[102:103], v[58:59], s[30:31]
	v_exp_f32_e32 v96, v96
	v_exp_f32_e32 v97, v97
	v_exp_f32_e32 v98, v98
	v_exp_f32_e32 v99, v99
	v_exp_f32_e32 v100, v100
	v_exp_f32_e32 v101, v101
	v_exp_f32_e32 v102, v102
	v_exp_f32_e32 v103, v103
	v_pk_add_f32 v[96:97], v[96:97], 1.0 op_sel_hi:[1,0]
	v_pk_add_f32 v[98:99], v[98:99], 1.0 op_sel_hi:[1,0]
	v_pk_add_f32 v[100:101], v[100:101], 1.0 op_sel_hi:[1,0]
	v_pk_add_f32 v[102:103], v[102:103], 1.0 op_sel_hi:[1,0]
	v_rcp_f32_e32 v96, v96
; __device__ __forceinline__ u32x4 pk8(f32x4 a, f32x4 b) { u32x4 w; w.x = pk2(a[0], a[1]); w.y = pk2(a[2], a[3]); w.z = pk2(b[0], b[1]); w.w = pk2(b[2], b[3]); return w; }
; __device__ __forceinline__ f32x4 silu4(f32x4 x) { f32x4 r; for (int i = 0; i < 4; ++i) r[i] = x[i] * sigm(x[i]); return r; }
; __device__ __forceinline__ float sigm(float x) { return __builtin_amdgcn_rcpf(1.f + __builtin_amdgcn_exp2f(-x * LOG2E)); }
;     __device__ __forceinline__ void operator()(const f32x4 (&acc)[2][2][4][2], const pg8::Unit& u, int wr, int wc, int fr_, int fq_) const {
;     ...
;                 } else if (pn < 5) {
;                     bf16_t* p = SGA + (size_t)row * 512 + (pn - 3) * 256 + cw;
;                     gst<u32x4>(p, pk8(silu4(a0), silu4(a1))); gst<u32x4>(p + 128, pk8(silu4(b0), silu4(b1)));
	v_rcp_f32_e32 v97, v97
	v_rcp_f32_e32 v98, v98
	v_rcp_f32_e32 v99, v99
	v_rcp_f32_e32 v100, v100
	v_rcp_f32_e32 v101, v101
	v_rcp_f32_e32 v102, v102
	v_rcp_f32_e32 v103, v103
	v_pk_mul_f32 v[60:61], v[60:61], v[96:97]
	v_pk_mul_f32 v[62:63], v[62:63], v[98:99]
	v_pk_mul_f32 v[56:57], v[56:57], v[100:101]
	v_pk_mul_f32 v[58:59], v[58:59], v[102:103]
	v_pk_mul_f32 v[96:97], v[52:53], s[30:31]
	v_pk_mul_f32 v[98:99], v[54:55], s[30:31]
	v_pk_mul_f32 v[100:101], v[48:49], s[30:31]
	v_pk_mul_f32 v[102:103], v[50:51], s[30:31]
	v_exp_f32_e32 v96, v96
	v_exp_f32_e32 v97, v97
	v_exp_f32_e32 v98, v98
	v_exp_f32_e32 v99, v99
	v_exp_f32_e32 v100, v100
	v_exp_f32_e32 v101, v101
	v_exp_f32_e32 v102, v102
	v_exp_f32_e32 v103, v103
	v_pk_add_f32 v[96:97], v[96:97], 1.0 op_sel_hi:[1,0]
	v_pk_add_f32 v[98:99], v[98:99], 1.0 op_sel_hi:[1,0]
	v_pk_add_f32 v[100:101], v[100:101], 1.0 op_sel_hi:[1,0]
	v_pk_add_f32 v[102:103], v[102:103], 1.0 op_sel_hi:[1,0]
	v_rcp_f32_e32 v96, v96
	v_rcp_f32_e32 v97, v97
	v_rcp_f32_e32 v98, v98
	v_rcp_f32_e32 v99, v99
	v_rcp_f32_e32 v100, v100
	v_rcp_f32_e32 v101, v101
	v_rcp_f32_e32 v102, v102
	v_rcp_f32_e32 v103, v103
	v_pk_mul_f32 v[52:53], v[52:53], v[96:97]
	v_pk_mul_f32 v[54:55], v[54:55], v[98:99]
	v_pk_mul_f32 v[48:49], v[48:49], v[100:101]
	v_pk_mul_f32 v[50:51], v[50:51], v[102:103]
	v_cvt_pk_bf16_f32 v104, v60, v61
	v_cvt_pk_bf16_f32 v105, v62, v63
	v_cvt_pk_bf16_f32 v106, v56, v57
	v_cvt_pk_bf16_f32 v107, v58, v59
	global_store_dwordx4 v214, v[104:107], s[16:17]
	v_cvt_pk_bf16_f32 v218, v52, v53
	v_cvt_pk_bf16_f32 v219, v54, v55
	v_cvt_pk_bf16_f32 v220, v48, v49
	v_cvt_pk_bf16_f32 v221, v50, v51
	global_store_dwordx4 v214, v[218:221], s[16:17] offset:256
	s_add_u32 s16, s16, 0x4000
	s_addc_u32 s17, s17, 0
	v_pk_mul_f32 v[44:45], v[44:45], v[186:187] op_sel_hi:[1,0]
	v_pk_mul_f32 v[46:47], v[46:47], v[186:187] op_sel_hi:[1,0]
	v_pk_mul_f32 v[40:41], v[40:41], v[186:187] op_sel_hi:[1,0]
	v_pk_mul_f32 v[42:43], v[42:43], v[186:187] op_sel_hi:[1,0]
	v_pk_mul_f32 v[36:37], v[36:37], v[186:187] op_sel_hi:[1,0]
	v_pk_mul_f32 v[38:39], v[38:39], v[186:187] op_sel_hi:[1,0]
	v_pk_mul_f32 v[32:33], v[32:33], v[186:187] op_sel_hi:[1,0]
	v_pk_mul_f32 v[34:35], v[34:35], v[186:187] op_sel_hi:[1,0]
	v_pk_mul_f32 v[96:97], v[44:45], s[30:31]
	v_pk_mul_f32 v[98:99], v[46:47], s[30:31]
	v_pk_mul_f32 v[100:101], v[40:41], s[30:31]
	v_pk_mul_f32 v[102:103], v[42:43], s[30:31]
	v_exp_f32_e32 v96, v96
	v_exp_f32_e32 v97, v97
	v_exp_f32_e32 v98, v98
	v_exp_f32_e32 v99, v99
	v_exp_f32_e32 v100, v100
	v_exp_f32_e32 v101, v101
	v_exp_f32_e32 v102, v102
	v_exp_f32_e32 v103, v103
	v_pk_add_f32 v[96:97], v[96:97], 1.0 op_sel_hi:[1,0]
	v_pk_add_f32 v[98:99], v[98:99], 1.0 op_sel_hi:[1,0]
	v_pk_add_f32 v[100:101], v[100:101], 1.0 op_sel_hi:[1,0]
	v_pk_add_f32 v[102:103], v[102:103], 1.0 op_sel_hi:[1,0]
	v_rcp_f32_e32 v96, v96
	v_rcp_f32_e32 v97, v97
	v_rcp_f32_e32 v98, v98
	v_rcp_f32_e32 v99, v99
	v_rcp_f32_e32 v100, v100
	v_rcp_f32_e32 v101, v101
	v_rcp_f32_e32 v102, v102
	v_rcp_f32_e32 v103, v103
	v_pk_mul_f32 v[44:45], v[44:45], v[96:97]
	v_pk_mul_f32 v[46:47], v[46:47], v[98:99]
	v_pk_mul_f32 v[40:41], v[40:41], v[100:101]
	v_pk_mul_f32 v[42:43], v[42:43], v[102:103]
	v_pk_mul_f32 v[96:97], v[36:37], s[30:31]
	v_pk_mul_f32 v[98:99], v[38:39], s[30:31]
	v_pk_mul_f32 v[100:101], v[32:33], s[30:31]
	v_pk_mul_f32 v[102:103], v[34:35], s[30:31]
	v_exp_f32_e32 v96, v96
	v_exp_f32_e32 v97, v97
	v_exp_f32_e32 v98, v98
	v_exp_f32_e32 v99, v99
	v_exp_f32_e32 v100, v100
	v_exp_f32_e32 v101, v101
	v_exp_f32_e32 v102, v102
	v_exp_f32_e32 v103, v103
	v_pk_add_f32 v[96:97], v[96:97], 1.0 op_sel_hi:[1,0]
	v_pk_add_f32 v[98:99], v[98:99], 1.0 op_sel_hi:[1,0]
	v_pk_add_f32 v[100:101], v[100:101], 1.0 op_sel_hi:[1,0]
	v_pk_add_f32 v[102:103], v[102:103], 1.0 op_sel_hi:[1,0]
	v_rcp_f32_e32 v96, v96
	v_rcp_f32_e32 v97, v97
	v_rcp_f32_e32 v98, v98
	v_rcp_f32_e32 v99, v99
	v_rcp_f32_e32 v100, v100
	v_rcp_f32_e32 v101, v101
	v_rcp_f32_e32 v102, v102
	v_rcp_f32_e32 v103, v103
	v_pk_mul_f32 v[36:37], v[36:37], v[96:97]
	v_pk_mul_f32 v[38:39], v[38:39], v[98:99]
	v_pk_mul_f32 v[32:33], v[32:33], v[100:101]
	v_pk_mul_f32 v[34:35], v[34:35], v[102:103]
	v_cvt_pk_bf16_f32 v108, v44, v45
	v_cvt_pk_bf16_f32 v109, v46, v47
	v_cvt_pk_bf16_f32 v110, v40, v41
	v_cvt_pk_bf16_f32 v111, v42, v43
	global_store_dwordx4 v214, v[108:111], s[16:17]
	v_cvt_pk_bf16_f32 v222, v36, v37
	v_cvt_pk_bf16_f32 v223, v38, v39
	v_cvt_pk_bf16_f32 v224, v32, v33
	v_cvt_pk_bf16_f32 v225, v34, v35
	global_store_dwordx4 v214, v[222:225], s[16:17] offset:256
	s_add_u32 s16, s16, 0x4000
	s_addc_u32 s17, s17, 0
	v_pk_mul_f32 v[28:29], v[28:29], v[188:189] op_sel_hi:[1,0]
	v_pk_mul_f32 v[30:31], v[30:31], v[188:189] op_sel_hi:[1,0]
	v_pk_mul_f32 v[24:25], v[24:25], v[188:189] op_sel_hi:[1,0]
	v_pk_mul_f32 v[26:27], v[26:27], v[188:189] op_sel_hi:[1,0]
	v_pk_mul_f32 v[20:21], v[20:21], v[188:189] op_sel_hi:[1,0]
	v_pk_mul_f32 v[22:23], v[22:23], v[188:189] op_sel_hi:[1,0]
	v_pk_mul_f32 v[16:17], v[16:17], v[188:189] op_sel_hi:[1,0]
	v_pk_mul_f32 v[18:19], v[18:19], v[188:189] op_sel_hi:[1,0]
	v_pk_mul_f32 v[96:97], v[28:29], s[30:31]
	v_pk_mul_f32 v[98:99], v[30:31], s[30:31]
	v_pk_mul_f32 v[100:101], v[24:25], s[30:31]
	v_pk_mul_f32 v[102:103], v[26:27], s[30:31]
	v_exp_f32_e32 v96, v96
	v_exp_f32_e32 v97, v97
	v_exp_f32_e32 v98, v98
	v_exp_f32_e32 v99, v99
	v_exp_f32_e32 v100, v100
	v_exp_f32_e32 v101, v101
	v_exp_f32_e32 v102, v102
	v_exp_f32_e32 v103, v103
	v_pk_add_f32 v[96:97], v[96:97], 1.0 op_sel_hi:[1,0]
	v_pk_add_f32 v[98:99], v[98:99], 1.0 op_sel_hi:[1,0]
	v_pk_add_f32 v[100:101], v[100:101], 1.0 op_sel_hi:[1,0]
; __device__ __forceinline__ u32x4 pk8(f32x4 a, f32x4 b) { u32x4 w; w.x = pk2(a[0], a[1]); w.y = pk2(a[2], a[3]); w.z = pk2(b[0], b[1]); w.w = pk2(b[2], b[3]); return w; }
; __device__ __forceinline__ f32x4 silu4(f32x4 x) { f32x4 r; for (int i = 0; i < 4; ++i) r[i] = x[i] * sigm(x[i]); return r; }
; __device__ __forceinline__ float sigm(float x) { return __builtin_amdgcn_rcpf(1.f + __builtin_amdgcn_exp2f(-x * LOG2E)); }
;     __device__ __forceinline__ void operator()(const f32x4 (&acc)[2][2][4][2], const pg8::Unit& u, int wr, int wc, int fr_, int fq_) const {
;     ...
;                 } else if (pn < 5) {
;                     bf16_t* p = SGA + (size_t)row * 512 + (pn - 3) * 256 + cw;
;                     gst<u32x4>(p, pk8(silu4(a0), silu4(a1))); gst<u32x4>(p + 128, pk8(silu4(b0), silu4(b1)));
	v_pk_add_f32 v[102:103], v[102:103], 1.0 op_sel_hi:[1,0]
	v_rcp_f32_e32 v96, v96
	v_rcp_f32_e32 v97, v97
	v_rcp_f32_e32 v98, v98
	v_rcp_f32_e32 v99, v99
	v_rcp_f32_e32 v100, v100
	v_rcp_f32_e32 v101, v101
	v_rcp_f32_e32 v102, v102
	v_rcp_f32_e32 v103, v103
	v_pk_mul_f32 v[28:29], v[28:29], v[96:97]
	v_pk_mul_f32 v[30:31], v[30:31], v[98:99]
	v_pk_mul_f32 v[24:25], v[24:25], v[100:101]
	v_pk_mul_f32 v[26:27], v[26:27], v[102:103]
	v_pk_mul_f32 v[96:97], v[20:21], s[30:31]
	v_pk_mul_f32 v[98:99], v[22:23], s[30:31]
	v_pk_mul_f32 v[100:101], v[16:17], s[30:31]
	v_pk_mul_f32 v[102:103], v[18:19], s[30:31]
	v_exp_f32_e32 v96, v96
	v_exp_f32_e32 v97, v97
	v_exp_f32_e32 v98, v98
	v_exp_f32_e32 v99, v99
	v_exp_f32_e32 v100, v100
	v_exp_f32_e32 v101, v101
	v_exp_f32_e32 v102, v102
	v_exp_f32_e32 v103, v103
	v_pk_add_f32 v[96:97], v[96:97], 1.0 op_sel_hi:[1,0]
	v_pk_add_f32 v[98:99], v[98:99], 1.0 op_sel_hi:[1,0]
	v_pk_add_f32 v[100:101], v[100:101], 1.0 op_sel_hi:[1,0]
	v_pk_add_f32 v[102:103], v[102:103], 1.0 op_sel_hi:[1,0]
	v_rcp_f32_e32 v96, v96
	v_rcp_f32_e32 v97, v97
	v_rcp_f32_e32 v98, v98
	v_rcp_f32_e32 v99, v99
	v_rcp_f32_e32 v100, v100
	v_rcp_f32_e32 v101, v101
	v_rcp_f32_e32 v102, v102
	v_rcp_f32_e32 v103, v103
	v_pk_mul_f32 v[20:21], v[20:21], v[96:97]
	v_pk_mul_f32 v[22:23], v[22:23], v[98:99]
	v_pk_mul_f32 v[16:17], v[16:17], v[100:101]
	v_pk_mul_f32 v[18:19], v[18:19], v[102:103]
	v_cvt_pk_bf16_f32 v104, v28, v29
	v_cvt_pk_bf16_f32 v105, v30, v31
	v_cvt_pk_bf16_f32 v106, v24, v25
	v_cvt_pk_bf16_f32 v107, v26, v27
	global_store_dwordx4 v214, v[104:107], s[16:17]
	v_cvt_pk_bf16_f32 v218, v20, v21
	v_cvt_pk_bf16_f32 v219, v22, v23
	v_cvt_pk_bf16_f32 v220, v16, v17
	v_cvt_pk_bf16_f32 v221, v18, v19
	global_store_dwordx4 v214, v[218:221], s[16:17] offset:256
	s_add_u32 s16, s16, 0x4000
	s_addc_u32 s17, s17, 0
	v_pk_mul_f32 v[12:13], v[12:13], v[190:191] op_sel_hi:[1,0]
	v_pk_mul_f32 v[14:15], v[14:15], v[190:191] op_sel_hi:[1,0]
	v_pk_mul_f32 v[8:9], v[8:9], v[190:191] op_sel_hi:[1,0]
	v_pk_mul_f32 v[10:11], v[10:11], v[190:191] op_sel_hi:[1,0]
	v_pk_mul_f32 v[4:5], v[4:5], v[190:191] op_sel_hi:[1,0]
	v_pk_mul_f32 v[6:7], v[6:7], v[190:191] op_sel_hi:[1,0]
	v_pk_mul_f32 v[0:1], v[0:1], v[190:191] op_sel_hi:[1,0]
	v_pk_mul_f32 v[2:3], v[2:3], v[190:191] op_sel_hi:[1,0]
	v_pk_mul_f32 v[96:97], v[12:13], s[30:31]
	v_pk_mul_f32 v[98:99], v[14:15], s[30:31]
	v_pk_mul_f32 v[100:101], v[8:9], s[30:31]
	v_pk_mul_f32 v[102:103], v[10:11], s[30:31]
	v_exp_f32_e32 v96, v96
	v_exp_f32_e32 v97, v97
	v_exp_f32_e32 v98, v98
	v_exp_f32_e32 v99, v99
	v_exp_f32_e32 v100, v100
	v_exp_f32_e32 v101, v101
	v_exp_f32_e32 v102, v102
	v_exp_f32_e32 v103, v103
	v_pk_add_f32 v[96:97], v[96:97], 1.0 op_sel_hi:[1,0]
	v_pk_add_f32 v[98:99], v[98:99], 1.0 op_sel_hi:[1,0]
	v_pk_add_f32 v[100:101], v[100:101], 1.0 op_sel_hi:[1,0]
	v_pk_add_f32 v[102:103], v[102:103], 1.0 op_sel_hi:[1,0]
	v_rcp_f32_e32 v96, v96
	v_rcp_f32_e32 v97, v97
	v_rcp_f32_e32 v98, v98
	v_rcp_f32_e32 v99, v99
	v_rcp_f32_e32 v100, v100
	v_rcp_f32_e32 v101, v101
	v_rcp_f32_e32 v102, v102
	v_rcp_f32_e32 v103, v103
	v_pk_mul_f32 v[12:13], v[12:13], v[96:97]
	v_pk_mul_f32 v[14:15], v[14:15], v[98:99]
	v_pk_mul_f32 v[8:9], v[8:9], v[100:101]
	v_pk_mul_f32 v[10:11], v[10:11], v[102:103]
	v_pk_mul_f32 v[96:97], v[4:5], s[30:31]
	v_pk_mul_f32 v[98:99], v[6:7], s[30:31]
	v_pk_mul_f32 v[100:101], v[0:1], s[30:31]
	v_pk_mul_f32 v[102:103], v[2:3], s[30:31]
	v_exp_f32_e32 v96, v96
	v_exp_f32_e32 v97, v97
	v_exp_f32_e32 v98, v98
	v_exp_f32_e32 v99, v99
	v_exp_f32_e32 v100, v100
	v_exp_f32_e32 v101, v101
	v_exp_f32_e32 v102, v102
	v_exp_f32_e32 v103, v103
	v_pk_add_f32 v[96:97], v[96:97], 1.0 op_sel_hi:[1,0]
	v_pk_add_f32 v[98:99], v[98:99], 1.0 op_sel_hi:[1,0]
	v_pk_add_f32 v[100:101], v[100:101], 1.0 op_sel_hi:[1,0]
	v_pk_add_f32 v[102:103], v[102:103], 1.0 op_sel_hi:[1,0]
	v_rcp_f32_e32 v96, v96
	v_rcp_f32_e32 v97, v97
	v_rcp_f32_e32 v98, v98
	v_rcp_f32_e32 v99, v99
	v_rcp_f32_e32 v100, v100
	v_rcp_f32_e32 v101, v101
	v_rcp_f32_e32 v102, v102
	v_rcp_f32_e32 v103, v103
	v_pk_mul_f32 v[4:5], v[4:5], v[96:97]
	v_pk_mul_f32 v[6:7], v[6:7], v[98:99]
	v_pk_mul_f32 v[0:1], v[0:1], v[100:101]
	v_pk_mul_f32 v[2:3], v[2:3], v[102:103]
	v_cvt_pk_bf16_f32 v108, v12, v13
	v_cvt_pk_bf16_f32 v109, v14, v15
	v_cvt_pk_bf16_f32 v110, v8, v9
	v_cvt_pk_bf16_f32 v111, v10, v11
	global_store_dwordx4 v214, v[108:111], s[16:17]
	v_cvt_pk_bf16_f32 v222, v4, v5
	v_cvt_pk_bf16_f32 v223, v6, v7
	v_cvt_pk_bf16_f32 v224, v0, v1
	v_cvt_pk_bf16_f32 v225, v2, v3
	global_store_dwordx4 v214, v[222:225], s[16:17] offset:256
	s_branch .LBB0_580
; __device__ __forceinline__ u32x4 pk8(f32x4 a, f32x4 b) { u32x4 w; w.x = pk2(a[0], a[1]); w.y = pk2(a[2], a[3]); w.z = pk2(b[0], b[1]); w.w = pk2(b[2], b[3]); return w; }
; __device__ __forceinline__ f32x4 silu4(f32x4 x) { f32x4 r; for (int i = 0; i < 4; ++i) r[i] = x[i] * sigm(x[i]); return r; }
;     __device__ __forceinline__ void operator()(const f32x4 (&acc)[2][2][4][2], const pg8::Unit& u, int wr, int wc, int fr_, int fq_) const {
;     ...
;                 } else if (pn < 9) {
;                     bf16_t* p = BGC + (size_t)row * 512 + (pn - 5) * 128 + cw;
;                     gst<u32x4>(p, pk8(a0 * silu4(b0), a1 * silu4(b1)));
.Lme_bpath:
	v_pk_mul_f32 v[132:133], v[132:133], v[176:177] op_sel_hi:[1,0]
	v_pk_mul_f32 v[134:135], v[134:135], v[176:177] op_sel_hi:[1,0]
	v_pk_mul_f32 v[128:129], v[128:129], v[176:177] op_sel_hi:[1,0]
	v_pk_mul_f32 v[130:131], v[130:131], v[176:177] op_sel_hi:[1,0]
	v_pk_mul_f32 v[116:117], v[116:117], v[176:177] op_sel_hi:[1,0]
	v_pk_mul_f32 v[118:119], v[118:119], v[176:177] op_sel_hi:[1,0]
	v_pk_mul_f32 v[112:113], v[112:113], v[176:177] op_sel_hi:[1,0]
	v_pk_mul_f32 v[114:115], v[114:115], v[176:177] op_sel_hi:[1,0]
	v_pk_mul_f32 v[96:97], v[116:117], s[30:31]
	v_pk_mul_f32 v[98:99], v[118:119], s[30:31]
	v_pk_mul_f32 v[100:101], v[112:113], s[30:31]
	v_pk_mul_f32 v[102:103], v[114:115], s[30:31]
	v_exp_f32_e32 v96, v96
	v_exp_f32_e32 v97, v97
	v_exp_f32_e32 v98, v98
	v_exp_f32_e32 v99, v99
	v_exp_f32_e32 v100, v100
	v_exp_f32_e32 v101, v101
	v_exp_f32_e32 v102, v102
	v_exp_f32_e32 v103, v103
	v_pk_add_f32 v[96:97], v[96:97], 1.0 op_sel_hi:[1,0]
	v_pk_add_f32 v[98:99], v[98:99], 1.0 op_sel_hi:[1,0]
	v_pk_add_f32 v[100:101], v[100:101], 1.0 op_sel_hi:[1,0]
	v_pk_add_f32 v[102:103], v[102:103], 1.0 op_sel_hi:[1,0]
	v_rcp_f32_e32 v96, v96
	v_rcp_f32_e32 v97, v97
	v_rcp_f32_e32 v98, v98
	v_rcp_f32_e32 v99, v99
	v_rcp_f32_e32 v100, v100
	v_rcp_f32_e32 v101, v101
	v_rcp_f32_e32 v102, v102
	v_rcp_f32_e32 v103, v103
	v_pk_mul_f32 v[96:97], v[116:117], v[96:97]
	v_pk_mul_f32 v[98:99], v[118:119], v[98:99]
	v_pk_mul_f32 v[100:101], v[112:113], v[100:101]
	v_pk_mul_f32 v[102:103], v[114:115], v[102:103]
	v_pk_mul_f32 v[132:133], v[132:133], v[96:97]
	v_pk_mul_f32 v[134:135], v[134:135], v[98:99]
	v_pk_mul_f32 v[128:129], v[128:129], v[100:101]
	v_pk_mul_f32 v[130:131], v[130:131], v[102:103]
	v_cvt_pk_bf16_f32 v104, v132, v133
	v_cvt_pk_bf16_f32 v105, v134, v135
	v_cvt_pk_bf16_f32 v106, v128, v129
	v_cvt_pk_bf16_f32 v107, v130, v131
	global_store_dwordx4 v214, v[104:107], s[16:17]
	s_add_u32 s16, s16, 0x4000
	s_addc_u32 s17, s17, 0
	v_pk_mul_f32 v[140:141], v[140:141], v[178:179] op_sel_hi:[1,0]
	v_pk_mul_f32 v[142:143], v[142:143], v[178:179] op_sel_hi:[1,0]
	v_pk_mul_f32 v[136:137], v[136:137], v[178:179] op_sel_hi:[1,0]
	v_pk_mul_f32 v[138:139], v[138:139], v[178:179] op_sel_hi:[1,0]
	v_pk_mul_f32 v[124:125], v[124:125], v[178:179] op_sel_hi:[1,0]
	v_pk_mul_f32 v[126:127], v[126:127], v[178:179] op_sel_hi:[1,0]
	v_pk_mul_f32 v[120:121], v[120:121], v[178:179] op_sel_hi:[1,0]
	v_pk_mul_f32 v[122:123], v[122:123], v[178:179] op_sel_hi:[1,0]
	v_pk_mul_f32 v[96:97], v[124:125], s[30:31]
	v_pk_mul_f32 v[98:99], v[126:127], s[30:31]
	v_pk_mul_f32 v[100:101], v[120:121], s[30:31]
	v_pk_mul_f32 v[102:103], v[122:123], s[30:31]
	v_exp_f32_e32 v96, v96
	v_exp_f32_e32 v97, v97
	v_exp_f32_e32 v98, v98
	v_exp_f32_e32 v99, v99
	v_exp_f32_e32 v100, v100
	v_exp_f32_e32 v101, v101
	v_exp_f32_e32 v102, v102
	v_exp_f32_e32 v103, v103
	v_pk_add_f32 v[96:97], v[96:97], 1.0 op_sel_hi:[1,0]
	v_pk_add_f32 v[98:99], v[98:99], 1.0 op_sel_hi:[1,0]
	v_pk_add_f32 v[100:101], v[100:101], 1.0 op_sel_hi:[1,0]
	v_pk_add_f32 v[102:103], v[102:103], 1.0 op_sel_hi:[1,0]
	v_rcp_f32_e32 v96, v96
	v_rcp_f32_e32 v97, v97
	v_rcp_f32_e32 v98, v98
	v_rcp_f32_e32 v99, v99
	v_rcp_f32_e32 v100, v100
	v_rcp_f32_e32 v101, v101
	v_rcp_f32_e32 v102, v102
	v_rcp_f32_e32 v103, v103
	v_pk_mul_f32 v[96:97], v[124:125], v[96:97]
	v_pk_mul_f32 v[98:99], v[126:127], v[98:99]
	v_pk_mul_f32 v[100:101], v[120:121], v[100:101]
	v_pk_mul_f32 v[102:103], v[122:123], v[102:103]
	v_pk_mul_f32 v[140:141], v[140:141], v[96:97]
	v_pk_mul_f32 v[142:143], v[142:143], v[98:99]
	v_pk_mul_f32 v[136:137], v[136:137], v[100:101]
	v_pk_mul_f32 v[138:139], v[138:139], v[102:103]
	v_cvt_pk_bf16_f32 v108, v140, v141
	v_cvt_pk_bf16_f32 v109, v142, v143
	v_cvt_pk_bf16_f32 v110, v136, v137
	v_cvt_pk_bf16_f32 v111, v138, v139
	global_store_dwordx4 v214, v[108:111], s[16:17]
	s_add_u32 s16, s16, 0x4000
	s_addc_u32 s17, s17, 0
	v_pk_mul_f32 v[92:93], v[92:93], v[180:181] op_sel_hi:[1,0]
	v_pk_mul_f32 v[94:95], v[94:95], v[180:181] op_sel_hi:[1,0]
	v_pk_mul_f32 v[88:89], v[88:89], v[180:181] op_sel_hi:[1,0]
	v_pk_mul_f32 v[90:91], v[90:91], v[180:181] op_sel_hi:[1,0]
	v_pk_mul_f32 v[84:85], v[84:85], v[180:181] op_sel_hi:[1,0]
	v_pk_mul_f32 v[86:87], v[86:87], v[180:181] op_sel_hi:[1,0]
	v_pk_mul_f32 v[80:81], v[80:81], v[180:181] op_sel_hi:[1,0]
	v_pk_mul_f32 v[82:83], v[82:83], v[180:181] op_sel_hi:[1,0]
	v_pk_mul_f32 v[96:97], v[84:85], s[30:31]
	v_pk_mul_f32 v[98:99], v[86:87], s[30:31]
	v_pk_mul_f32 v[100:101], v[80:81], s[30:31]
	v_pk_mul_f32 v[102:103], v[82:83], s[30:31]
	v_exp_f32_e32 v96, v96
	v_exp_f32_e32 v97, v97
	v_exp_f32_e32 v98, v98
	v_exp_f32_e32 v99, v99
	v_exp_f32_e32 v100, v100
	v_exp_f32_e32 v101, v101
	v_exp_f32_e32 v102, v102
	v_exp_f32_e32 v103, v103
	v_pk_add_f32 v[96:97], v[96:97], 1.0 op_sel_hi:[1,0]
	v_pk_add_f32 v[98:99], v[98:99], 1.0 op_sel_hi:[1,0]
	v_pk_add_f32 v[100:101], v[100:101], 1.0 op_sel_hi:[1,0]
	v_pk_add_f32 v[102:103], v[102:103], 1.0 op_sel_hi:[1,0]
	v_rcp_f32_e32 v96, v96
	v_rcp_f32_e32 v97, v97
	v_rcp_f32_e32 v98, v98
	v_rcp_f32_e32 v99, v99
	v_rcp_f32_e32 v100, v100
	v_rcp_f32_e32 v101, v101
	v_rcp_f32_e32 v102, v102
	v_rcp_f32_e32 v103, v103
	v_pk_mul_f32 v[96:97], v[84:85], v[96:97]
	v_pk_mul_f32 v[98:99], v[86:87], v[98:99]
	v_pk_mul_f32 v[100:101], v[80:81], v[100:101]
	v_pk_mul_f32 v[102:103], v[82:83], v[102:103]
	v_pk_mul_f32 v[92:93], v[92:93], v[96:97]
	v_pk_mul_f32 v[94:95], v[94:95], v[98:99]
	v_pk_mul_f32 v[88:89], v[88:89], v[100:101]
	v_pk_mul_f32 v[90:91], v[90:91], v[102:103]
	v_cvt_pk_bf16_f32 v104, v92, v93
	v_cvt_pk_bf16_f32 v105, v94, v95
; __device__ __forceinline__ u32x4 pk8(f32x4 a, f32x4 b) { u32x4 w; w.x = pk2(a[0], a[1]); w.y = pk2(a[2], a[3]); w.z = pk2(b[0], b[1]); w.w = pk2(b[2], b[3]); return w; }
; __device__ __forceinline__ f32x4 silu4(f32x4 x) { f32x4 r; for (int i = 0; i < 4; ++i) r[i] = x[i] * sigm(x[i]); return r; }
;     __device__ __forceinline__ void operator()(const f32x4 (&acc)[2][2][4][2], const pg8::Unit& u, int wr, int wc, int fr_, int fq_) const {
;     ...
;                 } else if (pn < 9) {
;                     bf16_t* p = BGC + (size_t)row * 512 + (pn - 5) * 128 + cw;
;                     gst<u32x4>(p, pk8(a0 * silu4(b0), a1 * silu4(b1)));
	v_cvt_pk_bf16_f32 v106, v88, v89
	v_cvt_pk_bf16_f32 v107, v90, v91
	global_store_dwordx4 v214, v[104:107], s[16:17]
	s_add_u32 s16, s16, 0x4000
	s_addc_u32 s17, s17, 0
	v_pk_mul_f32 v[76:77], v[76:77], v[182:183] op_sel_hi:[1,0]
	v_pk_mul_f32 v[78:79], v[78:79], v[182:183] op_sel_hi:[1,0]
	v_pk_mul_f32 v[72:73], v[72:73], v[182:183] op_sel_hi:[1,0]
	v_pk_mul_f32 v[74:75], v[74:75], v[182:183] op_sel_hi:[1,0]
	v_pk_mul_f32 v[68:69], v[68:69], v[182:183] op_sel_hi:[1,0]
	v_pk_mul_f32 v[70:71], v[70:71], v[182:183] op_sel_hi:[1,0]
	v_pk_mul_f32 v[64:65], v[64:65], v[182:183] op_sel_hi:[1,0]
	v_pk_mul_f32 v[66:67], v[66:67], v[182:183] op_sel_hi:[1,0]
	v_pk_mul_f32 v[96:97], v[68:69], s[30:31]
	v_pk_mul_f32 v[98:99], v[70:71], s[30:31]
	v_pk_mul_f32 v[100:101], v[64:65], s[30:31]
	v_pk_mul_f32 v[102:103], v[66:67], s[30:31]
	v_exp_f32_e32 v96, v96
	v_exp_f32_e32 v97, v97
	v_exp_f32_e32 v98, v98
	v_exp_f32_e32 v99, v99
	v_exp_f32_e32 v100, v100
	v_exp_f32_e32 v101, v101
	v_exp_f32_e32 v102, v102
	v_exp_f32_e32 v103, v103
	v_pk_add_f32 v[96:97], v[96:97], 1.0 op_sel_hi:[1,0]
	v_pk_add_f32 v[98:99], v[98:99], 1.0 op_sel_hi:[1,0]
	v_pk_add_f32 v[100:101], v[100:101], 1.0 op_sel_hi:[1,0]
	v_pk_add_f32 v[102:103], v[102:103], 1.0 op_sel_hi:[1,0]
	v_rcp_f32_e32 v96, v96
	v_rcp_f32_e32 v97, v97
	v_rcp_f32_e32 v98, v98
	v_rcp_f32_e32 v99, v99
	v_rcp_f32_e32 v100, v100
	v_rcp_f32_e32 v101, v101
	v_rcp_f32_e32 v102, v102
	v_rcp_f32_e32 v103, v103
	v_pk_mul_f32 v[96:97], v[68:69], v[96:97]
	v_pk_mul_f32 v[98:99], v[70:71], v[98:99]
	v_pk_mul_f32 v[100:101], v[64:65], v[100:101]
	v_pk_mul_f32 v[102:103], v[66:67], v[102:103]
	v_pk_mul_f32 v[76:77], v[76:77], v[96:97]
	v_pk_mul_f32 v[78:79], v[78:79], v[98:99]
	v_pk_mul_f32 v[72:73], v[72:73], v[100:101]
	v_pk_mul_f32 v[74:75], v[74:75], v[102:103]
	v_cvt_pk_bf16_f32 v108, v76, v77
	v_cvt_pk_bf16_f32 v109, v78, v79
	v_cvt_pk_bf16_f32 v110, v72, v73
	v_cvt_pk_bf16_f32 v111, v74, v75
	global_store_dwordx4 v214, v[108:111], s[16:17]
	s_add_u32 s16, s16, 0x14000
	s_addc_u32 s17, s17, 0
	v_pk_mul_f32 v[60:61], v[60:61], v[184:185] op_sel_hi:[1,0]
	v_pk_mul_f32 v[62:63], v[62:63], v[184:185] op_sel_hi:[1,0]
	v_pk_mul_f32 v[56:57], v[56:57], v[184:185] op_sel_hi:[1,0]
	v_pk_mul_f32 v[58:59], v[58:59], v[184:185] op_sel_hi:[1,0]
	v_pk_mul_f32 v[52:53], v[52:53], v[184:185] op_sel_hi:[1,0]
	v_pk_mul_f32 v[54:55], v[54:55], v[184:185] op_sel_hi:[1,0]
	v_pk_mul_f32 v[48:49], v[48:49], v[184:185] op_sel_hi:[1,0]
	v_pk_mul_f32 v[50:51], v[50:51], v[184:185] op_sel_hi:[1,0]
	v_pk_mul_f32 v[96:97], v[52:53], s[30:31]
	v_pk_mul_f32 v[98:99], v[54:55], s[30:31]
	v_pk_mul_f32 v[100:101], v[48:49], s[30:31]
	v_pk_mul_f32 v[102:103], v[50:51], s[30:31]
	v_exp_f32_e32 v96, v96
	v_exp_f32_e32 v97, v97
	v_exp_f32_e32 v98, v98
	v_exp_f32_e32 v99, v99
	v_exp_f32_e32 v100, v100
	v_exp_f32_e32 v101, v101
	v_exp_f32_e32 v102, v102
	v_exp_f32_e32 v103, v103
	v_pk_add_f32 v[96:97], v[96:97], 1.0 op_sel_hi:[1,0]
	v_pk_add_f32 v[98:99], v[98:99], 1.0 op_sel_hi:[1,0]
	v_pk_add_f32 v[100:101], v[100:101], 1.0 op_sel_hi:[1,0]
	v_pk_add_f32 v[102:103], v[102:103], 1.0 op_sel_hi:[1,0]
	v_rcp_f32_e32 v96, v96
	v_rcp_f32_e32 v97, v97
	v_rcp_f32_e32 v98, v98
	v_rcp_f32_e32 v99, v99
	v_rcp_f32_e32 v100, v100
	v_rcp_f32_e32 v101, v101
	v_rcp_f32_e32 v102, v102
	v_rcp_f32_e32 v103, v103
	v_pk_mul_f32 v[96:97], v[52:53], v[96:97]
	v_pk_mul_f32 v[98:99], v[54:55], v[98:99]
	v_pk_mul_f32 v[100:101], v[48:49], v[100:101]
	v_pk_mul_f32 v[102:103], v[50:51], v[102:103]
	v_pk_mul_f32 v[60:61], v[60:61], v[96:97]
	v_pk_mul_f32 v[62:63], v[62:63], v[98:99]
	v_pk_mul_f32 v[56:57], v[56:57], v[100:101]
	v_pk_mul_f32 v[58:59], v[58:59], v[102:103]
	v_cvt_pk_bf16_f32 v104, v60, v61
	v_cvt_pk_bf16_f32 v105, v62, v63
	v_cvt_pk_bf16_f32 v106, v56, v57
	v_cvt_pk_bf16_f32 v107, v58, v59
	global_store_dwordx4 v214, v[104:107], s[16:17]
	s_add_u32 s16, s16, 0x4000
	s_addc_u32 s17, s17, 0
	v_pk_mul_f32 v[44:45], v[44:45], v[186:187] op_sel_hi:[1,0]
	v_pk_mul_f32 v[46:47], v[46:47], v[186:187] op_sel_hi:[1,0]
	v_pk_mul_f32 v[40:41], v[40:41], v[186:187] op_sel_hi:[1,0]
	v_pk_mul_f32 v[42:43], v[42:43], v[186:187] op_sel_hi:[1,0]
	v_pk_mul_f32 v[36:37], v[36:37], v[186:187] op_sel_hi:[1,0]
	v_pk_mul_f32 v[38:39], v[38:39], v[186:187] op_sel_hi:[1,0]
	v_pk_mul_f32 v[32:33], v[32:33], v[186:187] op_sel_hi:[1,0]
	v_pk_mul_f32 v[34:35], v[34:35], v[186:187] op_sel_hi:[1,0]
	v_pk_mul_f32 v[96:97], v[36:37], s[30:31]
	v_pk_mul_f32 v[98:99], v[38:39], s[30:31]
	v_pk_mul_f32 v[100:101], v[32:33], s[30:31]
	v_pk_mul_f32 v[102:103], v[34:35], s[30:31]
	v_exp_f32_e32 v96, v96
	v_exp_f32_e32 v97, v97
	v_exp_f32_e32 v98, v98
	v_exp_f32_e32 v99, v99
	v_exp_f32_e32 v100, v100
	v_exp_f32_e32 v101, v101
	v_exp_f32_e32 v102, v102
	v_exp_f32_e32 v103, v103
	v_pk_add_f32 v[96:97], v[96:97], 1.0 op_sel_hi:[1,0]
	v_pk_add_f32 v[98:99], v[98:99], 1.0 op_sel_hi:[1,0]
	v_pk_add_f32 v[100:101], v[100:101], 1.0 op_sel_hi:[1,0]
	v_pk_add_f32 v[102:103], v[102:103], 1.0 op_sel_hi:[1,0]
	v_rcp_f32_e32 v96, v96
	v_rcp_f32_e32 v97, v97
	v_rcp_f32_e32 v98, v98
	v_rcp_f32_e32 v99, v99
	v_rcp_f32_e32 v100, v100
	v_rcp_f32_e32 v101, v101
	v_rcp_f32_e32 v102, v102
	v_rcp_f32_e32 v103, v103
	v_pk_mul_f32 v[96:97], v[36:37], v[96:97]
	v_pk_mul_f32 v[98:99], v[38:39], v[98:99]
	v_pk_mul_f32 v[100:101], v[32:33], v[100:101]
	v_pk_mul_f32 v[102:103], v[34:35], v[102:103]
	v_pk_mul_f32 v[44:45], v[44:45], v[96:97]
	v_pk_mul_f32 v[46:47], v[46:47], v[98:99]
	v_pk_mul_f32 v[40:41], v[40:41], v[100:101]
	v_pk_mul_f32 v[42:43], v[42:43], v[102:103]
	v_cvt_pk_bf16_f32 v108, v44, v45
	v_cvt_pk_bf16_f32 v109, v46, v47
; __device__ __forceinline__ u32x4 pk8(f32x4 a, f32x4 b) { u32x4 w; w.x = pk2(a[0], a[1]); w.y = pk2(a[2], a[3]); w.z = pk2(b[0], b[1]); w.w = pk2(b[2], b[3]); return w; }
; __device__ __forceinline__ f32x4 silu4(f32x4 x) { f32x4 r; for (int i = 0; i < 4; ++i) r[i] = x[i] * sigm(x[i]); return r; }
;     __device__ __forceinline__ void operator()(const f32x4 (&acc)[2][2][4][2], const pg8::Unit& u, int wr, int wc, int fr_, int fq_) const {
;     ...
;                 } else if (pn < 9) {
;                     bf16_t* p = BGC + (size_t)row * 512 + (pn - 5) * 128 + cw;
;                     gst<u32x4>(p, pk8(a0 * silu4(b0), a1 * silu4(b1)));
;                 } else {
;                     const f32x4 u0 = a0 * b0, u1 = a1 * b1; const int c = (pn - 9) * 128 + cw;
;                     gst<u32x4>(U + (size_t)row * 512 + c, pk8(u0, u1));
;                     const bool smp = row >= NPR; const bool wr_out = smp ? (row & 3) >= 2 : (row & 2047) >= 2046;
;                     const size_t uofs = smp ? O_NCS + ((size_t)(L * 128 + ((row - NPR) >> 2)) * 2 + ((row & 3) - 2)) * 512 : O_NCP + ((size_t)(L * 8 + (row >> 11)) * 2 + ((row & 2047) - 2046)) * 512;
;                     if (wr_out) { float* uo = out + uofs + c; gst<f32x4>(uo, u0); gst<f32x4>(uo + 4, u1); }
	v_cvt_pk_bf16_f32 v110, v40, v41
	v_cvt_pk_bf16_f32 v111, v42, v43
	global_store_dwordx4 v214, v[108:111], s[16:17]
	s_add_u32 s16, s16, 0x4000
	s_addc_u32 s17, s17, 0
	v_pk_mul_f32 v[28:29], v[28:29], v[188:189] op_sel_hi:[1,0]
	v_pk_mul_f32 v[30:31], v[30:31], v[188:189] op_sel_hi:[1,0]
	v_pk_mul_f32 v[24:25], v[24:25], v[188:189] op_sel_hi:[1,0]
	v_pk_mul_f32 v[26:27], v[26:27], v[188:189] op_sel_hi:[1,0]
	v_pk_mul_f32 v[20:21], v[20:21], v[188:189] op_sel_hi:[1,0]
	v_pk_mul_f32 v[22:23], v[22:23], v[188:189] op_sel_hi:[1,0]
	v_pk_mul_f32 v[16:17], v[16:17], v[188:189] op_sel_hi:[1,0]
	v_pk_mul_f32 v[18:19], v[18:19], v[188:189] op_sel_hi:[1,0]
	v_pk_mul_f32 v[96:97], v[20:21], s[30:31]
	v_pk_mul_f32 v[98:99], v[22:23], s[30:31]
	v_pk_mul_f32 v[100:101], v[16:17], s[30:31]
	v_pk_mul_f32 v[102:103], v[18:19], s[30:31]
	v_exp_f32_e32 v96, v96
	v_exp_f32_e32 v97, v97
	v_exp_f32_e32 v98, v98
	v_exp_f32_e32 v99, v99
	v_exp_f32_e32 v100, v100
	v_exp_f32_e32 v101, v101
	v_exp_f32_e32 v102, v102
	v_exp_f32_e32 v103, v103
	v_pk_add_f32 v[96:97], v[96:97], 1.0 op_sel_hi:[1,0]
	v_pk_add_f32 v[98:99], v[98:99], 1.0 op_sel_hi:[1,0]
	v_pk_add_f32 v[100:101], v[100:101], 1.0 op_sel_hi:[1,0]
	v_pk_add_f32 v[102:103], v[102:103], 1.0 op_sel_hi:[1,0]
	v_rcp_f32_e32 v96, v96
	v_rcp_f32_e32 v97, v97
	v_rcp_f32_e32 v98, v98
	v_rcp_f32_e32 v99, v99
	v_rcp_f32_e32 v100, v100
	v_rcp_f32_e32 v101, v101
	v_rcp_f32_e32 v102, v102
	v_rcp_f32_e32 v103, v103
	v_pk_mul_f32 v[96:97], v[20:21], v[96:97]
	v_pk_mul_f32 v[98:99], v[22:23], v[98:99]
	v_pk_mul_f32 v[100:101], v[16:17], v[100:101]
	v_pk_mul_f32 v[102:103], v[18:19], v[102:103]
	v_pk_mul_f32 v[28:29], v[28:29], v[96:97]
	v_pk_mul_f32 v[30:31], v[30:31], v[98:99]
	v_pk_mul_f32 v[24:25], v[24:25], v[100:101]
	v_pk_mul_f32 v[26:27], v[26:27], v[102:103]
	v_cvt_pk_bf16_f32 v104, v28, v29
	v_cvt_pk_bf16_f32 v105, v30, v31
	v_cvt_pk_bf16_f32 v106, v24, v25
	v_cvt_pk_bf16_f32 v107, v26, v27
	global_store_dwordx4 v214, v[104:107], s[16:17]
	s_add_u32 s16, s16, 0x4000
	s_addc_u32 s17, s17, 0
	v_pk_mul_f32 v[12:13], v[12:13], v[190:191] op_sel_hi:[1,0]
	v_pk_mul_f32 v[14:15], v[14:15], v[190:191] op_sel_hi:[1,0]
	v_pk_mul_f32 v[8:9], v[8:9], v[190:191] op_sel_hi:[1,0]
	v_pk_mul_f32 v[10:11], v[10:11], v[190:191] op_sel_hi:[1,0]
	v_pk_mul_f32 v[4:5], v[4:5], v[190:191] op_sel_hi:[1,0]
	v_pk_mul_f32 v[6:7], v[6:7], v[190:191] op_sel_hi:[1,0]
	v_pk_mul_f32 v[0:1], v[0:1], v[190:191] op_sel_hi:[1,0]
	v_pk_mul_f32 v[2:3], v[2:3], v[190:191] op_sel_hi:[1,0]
	v_pk_mul_f32 v[96:97], v[4:5], s[30:31]
	v_pk_mul_f32 v[98:99], v[6:7], s[30:31]
	v_pk_mul_f32 v[100:101], v[0:1], s[30:31]
	v_pk_mul_f32 v[102:103], v[2:3], s[30:31]
	v_exp_f32_e32 v96, v96
	v_exp_f32_e32 v97, v97
	v_exp_f32_e32 v98, v98
	v_exp_f32_e32 v99, v99
	v_exp_f32_e32 v100, v100
	v_exp_f32_e32 v101, v101
	v_exp_f32_e32 v102, v102
	v_exp_f32_e32 v103, v103
	v_pk_add_f32 v[96:97], v[96:97], 1.0 op_sel_hi:[1,0]
	v_pk_add_f32 v[98:99], v[98:99], 1.0 op_sel_hi:[1,0]
	v_pk_add_f32 v[100:101], v[100:101], 1.0 op_sel_hi:[1,0]
	v_pk_add_f32 v[102:103], v[102:103], 1.0 op_sel_hi:[1,0]
	v_rcp_f32_e32 v96, v96
	v_rcp_f32_e32 v97, v97
	v_rcp_f32_e32 v98, v98
	v_rcp_f32_e32 v99, v99
	v_rcp_f32_e32 v100, v100
	v_rcp_f32_e32 v101, v101
	v_rcp_f32_e32 v102, v102
	v_rcp_f32_e32 v103, v103
	v_pk_mul_f32 v[96:97], v[4:5], v[96:97]
	v_pk_mul_f32 v[98:99], v[6:7], v[98:99]
	v_pk_mul_f32 v[100:101], v[0:1], v[100:101]
	v_pk_mul_f32 v[102:103], v[2:3], v[102:103]
	v_pk_mul_f32 v[12:13], v[12:13], v[96:97]
	v_pk_mul_f32 v[14:15], v[14:15], v[98:99]
	v_pk_mul_f32 v[8:9], v[8:9], v[100:101]
	v_pk_mul_f32 v[10:11], v[10:11], v[102:103]
	v_cvt_pk_bf16_f32 v108, v12, v13
	v_cvt_pk_bf16_f32 v109, v14, v15
	v_cvt_pk_bf16_f32 v110, v8, v9
	v_cvt_pk_bf16_f32 v111, v10, v11
	global_store_dwordx4 v214, v[108:111], s[16:17]
	s_branch .LBB0_580
.Lme_upath:
	s_mov_b64 s[18:19], 0
	s_mov_b32 s7, 0
	s_cmp_gt_i32 s4, 63
	s_cbranch_scc1 .Lme_smpunit
	s_and_b32 s5, s4, 7
	s_cmp_eq_u32 s5, 7
	s_cbranch_scc0 .Lme_fdone
	s_cmp_eq_u32 s89, 64
	s_cbranch_scc0 .Lme_fdone
	s_mov_b32 s7, 2
	v_and_b32_e32 v215, 15, v248
	v_cmp_lt_u32_e64 s[18:19], 13, v215
	v_add_u32_e32 v216, -14, v215
	v_lshlrev_b32_e32 v216, 11, v216
	v_lshl_add_u32 v216, v211, 5, v216
	s_lshl_b32 s5, s20, 3
	s_lshr_b32 s8, s4, 3
	s_add_i32 s5, s5, s8
	s_lshl_b32 s5, s5, 12
	s_add_u32 s5, s5, 0x45d4000
	s_branch .Lme_fbase
.Lme_smpunit:
	s_mov_b32 s7, 1
	v_and_b32_e32 v215, 3, v248
	v_cmp_lt_u32_e64 s[18:19], 1, v215
	v_add_u32_e32 v216, -2, v215
	v_lshlrev_b32_e32 v216, 11, v216
	v_lshl_add_u32 v216, v211, 5, v216
	v_add_u32_e32 v217, 0xffffc000, v210
	v_lshrrev_b32_e32 v217, 2, v217
	v_lshl_add_u32 v216, v217, 12, v216
	s_lshl_b32 s5, s20, 19
	s_add_u32 s5, s5, 0x8620000
.Lme_fbase:
	s_add_i32 s8, s6, -9
	s_lshl_b32 s8, s8, 9
	s_add_i32 s5, s5, s8
	s_lshl_b32 s8, s93, 1
	s_add_i32 s5, s5, s8
	s_add_u32 s8, s28, s5
	s_addc_u32 s9, s29, 0
.Lme_fdone:
	v_pk_mul_f32 v[132:133], v[132:133], v[176:177] op_sel_hi:[1,0]
	v_pk_mul_f32 v[134:135], v[134:135], v[176:177] op_sel_hi:[1,0]
	v_pk_mul_f32 v[128:129], v[128:129], v[176:177] op_sel_hi:[1,0]
	v_pk_mul_f32 v[130:131], v[130:131], v[176:177] op_sel_hi:[1,0]
	v_pk_mul_f32 v[116:117], v[116:117], v[176:177] op_sel_hi:[1,0]
	v_pk_mul_f32 v[118:119], v[118:119], v[176:177] op_sel_hi:[1,0]
	v_pk_mul_f32 v[112:113], v[112:113], v[176:177] op_sel_hi:[1,0]
	v_pk_mul_f32 v[114:115], v[114:115], v[176:177] op_sel_hi:[1,0]
	v_pk_mul_f32 v[132:133], v[132:133], v[116:117]
	v_pk_mul_f32 v[134:135], v[134:135], v[118:119]
	v_pk_mul_f32 v[128:129], v[128:129], v[112:113]
	v_pk_mul_f32 v[130:131], v[130:131], v[114:115]
	s_cmp_eq_u32 s7, 1
	s_cbranch_scc0 .Lme_nof32_0
; __device__ __forceinline__ u32x4 pk8(f32x4 a, f32x4 b) { u32x4 w; w.x = pk2(a[0], a[1]); w.y = pk2(a[2], a[3]); w.z = pk2(b[0], b[1]); w.w = pk2(b[2], b[3]); return w; }
;     __device__ __forceinline__ void operator()(const f32x4 (&acc)[2][2][4][2], const pg8::Unit& u, int wr, int wc, int fr_, int fq_) const {
;     ...
;                 } else {
;                     const f32x4 u0 = a0 * b0, u1 = a1 * b1; const int c = (pn - 9) * 128 + cw;
;                     gst<u32x4>(U + (size_t)row * 512 + c, pk8(u0, u1));
;                     const bool smp = row >= NPR; const bool wr_out = smp ? (row & 3) >= 2 : (row & 2047) >= 2046;
;                     const size_t uofs = smp ? O_NCS + ((size_t)(L * 128 + ((row - NPR) >> 2)) * 2 + ((row & 3) - 2)) * 512 : O_NCP + ((size_t)(L * 8 + (row >> 11)) * 2 + ((row & 2047) - 2046)) * 512;
;                     if (wr_out) { float* uo = out + uofs + c; gst<f32x4>(uo, u0); gst<f32x4>(uo + 4, u1); }
.Lme_f32_0:
	s_mov_b64 s[12:13], exec
	s_and_b64 exec, exec, s[18:19]
	global_store_dwordx4 v216, v[132:135], s[8:9]
	global_store_dwordx4 v216, v[128:131], s[8:9] offset:16
	s_mov_b64 exec, s[12:13]
.Lme_nof32_0:
	v_cvt_pk_bf16_f32 v104, v132, v133
	v_cvt_pk_bf16_f32 v105, v134, v135
	v_cvt_pk_bf16_f32 v106, v128, v129
	v_cvt_pk_bf16_f32 v107, v130, v131
	global_store_dwordx4 v214, v[104:107], s[16:17]
	s_add_u32 s16, s16, 0x4000
	s_addc_u32 s17, s17, 0
	s_add_u32 s8, s8, 0x4000
	s_addc_u32 s9, s9, 0
	v_pk_mul_f32 v[140:141], v[140:141], v[178:179] op_sel_hi:[1,0]
	v_pk_mul_f32 v[142:143], v[142:143], v[178:179] op_sel_hi:[1,0]
	v_pk_mul_f32 v[136:137], v[136:137], v[178:179] op_sel_hi:[1,0]
	v_pk_mul_f32 v[138:139], v[138:139], v[178:179] op_sel_hi:[1,0]
	v_pk_mul_f32 v[124:125], v[124:125], v[178:179] op_sel_hi:[1,0]
	v_pk_mul_f32 v[126:127], v[126:127], v[178:179] op_sel_hi:[1,0]
	v_pk_mul_f32 v[120:121], v[120:121], v[178:179] op_sel_hi:[1,0]
	v_pk_mul_f32 v[122:123], v[122:123], v[178:179] op_sel_hi:[1,0]
	v_pk_mul_f32 v[140:141], v[140:141], v[124:125]
	v_pk_mul_f32 v[142:143], v[142:143], v[126:127]
	v_pk_mul_f32 v[136:137], v[136:137], v[120:121]
	v_pk_mul_f32 v[138:139], v[138:139], v[122:123]
	s_cmp_eq_u32 s7, 1
	s_cbranch_scc0 .Lme_nof32_1
.Lme_f32_1:
	s_mov_b64 s[12:13], exec
	s_and_b64 exec, exec, s[18:19]
	global_store_dwordx4 v216, v[140:143], s[8:9]
	global_store_dwordx4 v216, v[136:139], s[8:9] offset:16
	s_mov_b64 exec, s[12:13]
.Lme_nof32_1:
	v_cvt_pk_bf16_f32 v108, v140, v141
	v_cvt_pk_bf16_f32 v109, v142, v143
	v_cvt_pk_bf16_f32 v110, v136, v137
	v_cvt_pk_bf16_f32 v111, v138, v139
	global_store_dwordx4 v214, v[108:111], s[16:17]
	s_add_u32 s16, s16, 0x4000
	s_addc_u32 s17, s17, 0
	s_add_u32 s8, s8, 0x4000
	s_addc_u32 s9, s9, 0
	v_pk_mul_f32 v[92:93], v[92:93], v[180:181] op_sel_hi:[1,0]
	v_pk_mul_f32 v[94:95], v[94:95], v[180:181] op_sel_hi:[1,0]
	v_pk_mul_f32 v[88:89], v[88:89], v[180:181] op_sel_hi:[1,0]
	v_pk_mul_f32 v[90:91], v[90:91], v[180:181] op_sel_hi:[1,0]
	v_pk_mul_f32 v[84:85], v[84:85], v[180:181] op_sel_hi:[1,0]
	v_pk_mul_f32 v[86:87], v[86:87], v[180:181] op_sel_hi:[1,0]
	v_pk_mul_f32 v[80:81], v[80:81], v[180:181] op_sel_hi:[1,0]
	v_pk_mul_f32 v[82:83], v[82:83], v[180:181] op_sel_hi:[1,0]
	v_pk_mul_f32 v[92:93], v[92:93], v[84:85]
	v_pk_mul_f32 v[94:95], v[94:95], v[86:87]
	v_pk_mul_f32 v[88:89], v[88:89], v[80:81]
	v_pk_mul_f32 v[90:91], v[90:91], v[82:83]
	s_cmp_eq_u32 s7, 1
	s_cbranch_scc0 .Lme_nof32_2
.Lme_f32_2:
	s_mov_b64 s[12:13], exec
	s_and_b64 exec, exec, s[18:19]
	global_store_dwordx4 v216, v[92:95], s[8:9]
	global_store_dwordx4 v216, v[88:91], s[8:9] offset:16
	s_mov_b64 exec, s[12:13]
.Lme_nof32_2:
	v_cvt_pk_bf16_f32 v104, v92, v93
	v_cvt_pk_bf16_f32 v105, v94, v95
	v_cvt_pk_bf16_f32 v106, v88, v89
	v_cvt_pk_bf16_f32 v107, v90, v91
	global_store_dwordx4 v214, v[104:107], s[16:17]
	s_add_u32 s16, s16, 0x4000
	s_addc_u32 s17, s17, 0
	s_add_u32 s8, s8, 0x4000
	s_addc_u32 s9, s9, 0
	v_pk_mul_f32 v[76:77], v[76:77], v[182:183] op_sel_hi:[1,0]
	v_pk_mul_f32 v[78:79], v[78:79], v[182:183] op_sel_hi:[1,0]
	v_pk_mul_f32 v[72:73], v[72:73], v[182:183] op_sel_hi:[1,0]
	v_pk_mul_f32 v[74:75], v[74:75], v[182:183] op_sel_hi:[1,0]
	v_pk_mul_f32 v[68:69], v[68:69], v[182:183] op_sel_hi:[1,0]
	v_pk_mul_f32 v[70:71], v[70:71], v[182:183] op_sel_hi:[1,0]
	v_pk_mul_f32 v[64:65], v[64:65], v[182:183] op_sel_hi:[1,0]
	v_pk_mul_f32 v[66:67], v[66:67], v[182:183] op_sel_hi:[1,0]
	v_pk_mul_f32 v[76:77], v[76:77], v[68:69]
	v_pk_mul_f32 v[78:79], v[78:79], v[70:71]
	v_pk_mul_f32 v[72:73], v[72:73], v[64:65]
	v_pk_mul_f32 v[74:75], v[74:75], v[66:67]
	s_cmp_eq_u32 s7, 1
	s_cbranch_scc0 .Lme_nof32_3
.Lme_f32_3:
	s_mov_b64 s[12:13], exec
	s_and_b64 exec, exec, s[18:19]
	global_store_dwordx4 v216, v[76:79], s[8:9]
	global_store_dwordx4 v216, v[72:75], s[8:9] offset:16
	s_mov_b64 exec, s[12:13]
.Lme_nof32_3:
	v_cvt_pk_bf16_f32 v108, v76, v77
	v_cvt_pk_bf16_f32 v109, v78, v79
	v_cvt_pk_bf16_f32 v110, v72, v73
	v_cvt_pk_bf16_f32 v111, v74, v75
	global_store_dwordx4 v214, v[108:111], s[16:17]
	s_add_u32 s16, s16, 0x14000
	s_addc_u32 s17, s17, 0
	s_add_u32 s8, s8, 0x14000
	s_addc_u32 s9, s9, 0
	v_pk_mul_f32 v[60:61], v[60:61], v[184:185] op_sel_hi:[1,0]
	v_pk_mul_f32 v[62:63], v[62:63], v[184:185] op_sel_hi:[1,0]
	v_pk_mul_f32 v[56:57], v[56:57], v[184:185] op_sel_hi:[1,0]
	v_pk_mul_f32 v[58:59], v[58:59], v[184:185] op_sel_hi:[1,0]
	v_pk_mul_f32 v[52:53], v[52:53], v[184:185] op_sel_hi:[1,0]
	v_pk_mul_f32 v[54:55], v[54:55], v[184:185] op_sel_hi:[1,0]
	v_pk_mul_f32 v[48:49], v[48:49], v[184:185] op_sel_hi:[1,0]
	v_pk_mul_f32 v[50:51], v[50:51], v[184:185] op_sel_hi:[1,0]
	v_pk_mul_f32 v[60:61], v[60:61], v[52:53]
	v_pk_mul_f32 v[62:63], v[62:63], v[54:55]
	v_pk_mul_f32 v[56:57], v[56:57], v[48:49]
	v_pk_mul_f32 v[58:59], v[58:59], v[50:51]
	s_cmp_eq_u32 s7, 1
	s_cbranch_scc0 .Lme_nof32_4
; __device__ __forceinline__ u32x4 pk8(f32x4 a, f32x4 b) { u32x4 w; w.x = pk2(a[0], a[1]); w.y = pk2(a[2], a[3]); w.z = pk2(b[0], b[1]); w.w = pk2(b[2], b[3]); return w; }
;     __device__ __forceinline__ void operator()(const f32x4 (&acc)[2][2][4][2], const pg8::Unit& u, int wr, int wc, int fr_, int fq_) const {
;     ...
;                 } else {
;                     const f32x4 u0 = a0 * b0, u1 = a1 * b1; const int c = (pn - 9) * 128 + cw;
;                     gst<u32x4>(U + (size_t)row * 512 + c, pk8(u0, u1));
;                     const bool smp = row >= NPR; const bool wr_out = smp ? (row & 3) >= 2 : (row & 2047) >= 2046;
;                     const size_t uofs = smp ? O_NCS + ((size_t)(L * 128 + ((row - NPR) >> 2)) * 2 + ((row & 3) - 2)) * 512 : O_NCP + ((size_t)(L * 8 + (row >> 11)) * 2 + ((row & 2047) - 2046)) * 512;
;                     if (wr_out) { float* uo = out + uofs + c; gst<f32x4>(uo, u0); gst<f32x4>(uo + 4, u1); }
.Lme_f32_4:
	s_mov_b64 s[12:13], exec
	s_and_b64 exec, exec, s[18:19]
	global_store_dwordx4 v216, v[60:63], s[8:9]
	global_store_dwordx4 v216, v[56:59], s[8:9] offset:16
	s_mov_b64 exec, s[12:13]
.Lme_nof32_4:
	v_cvt_pk_bf16_f32 v104, v60, v61
	v_cvt_pk_bf16_f32 v105, v62, v63
	v_cvt_pk_bf16_f32 v106, v56, v57
	v_cvt_pk_bf16_f32 v107, v58, v59
	global_store_dwordx4 v214, v[104:107], s[16:17]
	s_add_u32 s16, s16, 0x4000
	s_addc_u32 s17, s17, 0
	s_add_u32 s8, s8, 0x4000
	s_addc_u32 s9, s9, 0
	v_pk_mul_f32 v[44:45], v[44:45], v[186:187] op_sel_hi:[1,0]
	v_pk_mul_f32 v[46:47], v[46:47], v[186:187] op_sel_hi:[1,0]
	v_pk_mul_f32 v[40:41], v[40:41], v[186:187] op_sel_hi:[1,0]
	v_pk_mul_f32 v[42:43], v[42:43], v[186:187] op_sel_hi:[1,0]
	v_pk_mul_f32 v[36:37], v[36:37], v[186:187] op_sel_hi:[1,0]
	v_pk_mul_f32 v[38:39], v[38:39], v[186:187] op_sel_hi:[1,0]
	v_pk_mul_f32 v[32:33], v[32:33], v[186:187] op_sel_hi:[1,0]
	v_pk_mul_f32 v[34:35], v[34:35], v[186:187] op_sel_hi:[1,0]
	v_pk_mul_f32 v[44:45], v[44:45], v[36:37]
	v_pk_mul_f32 v[46:47], v[46:47], v[38:39]
	v_pk_mul_f32 v[40:41], v[40:41], v[32:33]
	v_pk_mul_f32 v[42:43], v[42:43], v[34:35]
	s_cmp_eq_u32 s7, 1
	s_cbranch_scc0 .Lme_nof32_5
.Lme_f32_5:
	s_mov_b64 s[12:13], exec
	s_and_b64 exec, exec, s[18:19]
	global_store_dwordx4 v216, v[44:47], s[8:9]
	global_store_dwordx4 v216, v[40:43], s[8:9] offset:16
	s_mov_b64 exec, s[12:13]
.Lme_nof32_5:
	v_cvt_pk_bf16_f32 v108, v44, v45
	v_cvt_pk_bf16_f32 v109, v46, v47
	v_cvt_pk_bf16_f32 v110, v40, v41
	v_cvt_pk_bf16_f32 v111, v42, v43
	global_store_dwordx4 v214, v[108:111], s[16:17]
	s_add_u32 s16, s16, 0x4000
	s_addc_u32 s17, s17, 0
	s_add_u32 s8, s8, 0x4000
	s_addc_u32 s9, s9, 0
	v_pk_mul_f32 v[28:29], v[28:29], v[188:189] op_sel_hi:[1,0]
	v_pk_mul_f32 v[30:31], v[30:31], v[188:189] op_sel_hi:[1,0]
	v_pk_mul_f32 v[24:25], v[24:25], v[188:189] op_sel_hi:[1,0]
	v_pk_mul_f32 v[26:27], v[26:27], v[188:189] op_sel_hi:[1,0]
	v_pk_mul_f32 v[20:21], v[20:21], v[188:189] op_sel_hi:[1,0]
	v_pk_mul_f32 v[22:23], v[22:23], v[188:189] op_sel_hi:[1,0]
	v_pk_mul_f32 v[16:17], v[16:17], v[188:189] op_sel_hi:[1,0]
	v_pk_mul_f32 v[18:19], v[18:19], v[188:189] op_sel_hi:[1,0]
	v_pk_mul_f32 v[28:29], v[28:29], v[20:21]
	v_pk_mul_f32 v[30:31], v[30:31], v[22:23]
	v_pk_mul_f32 v[24:25], v[24:25], v[16:17]
	v_pk_mul_f32 v[26:27], v[26:27], v[18:19]
	s_cmp_eq_u32 s7, 1
	s_cbranch_scc0 .Lme_nof32_6
.Lme_f32_6:
	s_mov_b64 s[12:13], exec
	s_and_b64 exec, exec, s[18:19]
	global_store_dwordx4 v216, v[28:31], s[8:9]
	global_store_dwordx4 v216, v[24:27], s[8:9] offset:16
	s_mov_b64 exec, s[12:13]
.Lme_nof32_6:
	v_cvt_pk_bf16_f32 v104, v28, v29
	v_cvt_pk_bf16_f32 v105, v30, v31
	v_cvt_pk_bf16_f32 v106, v24, v25
	v_cvt_pk_bf16_f32 v107, v26, v27
	global_store_dwordx4 v214, v[104:107], s[16:17]
	s_add_u32 s16, s16, 0x4000
	s_addc_u32 s17, s17, 0
	s_add_u32 s8, s8, 0x4000
	s_addc_u32 s9, s9, 0
	v_pk_mul_f32 v[12:13], v[12:13], v[190:191] op_sel_hi:[1,0]
	v_pk_mul_f32 v[14:15], v[14:15], v[190:191] op_sel_hi:[1,0]
	v_pk_mul_f32 v[8:9], v[8:9], v[190:191] op_sel_hi:[1,0]
	v_pk_mul_f32 v[10:11], v[10:11], v[190:191] op_sel_hi:[1,0]
	v_pk_mul_f32 v[4:5], v[4:5], v[190:191] op_sel_hi:[1,0]
	v_pk_mul_f32 v[6:7], v[6:7], v[190:191] op_sel_hi:[1,0]
	v_pk_mul_f32 v[0:1], v[0:1], v[190:191] op_sel_hi:[1,0]
	v_pk_mul_f32 v[2:3], v[2:3], v[190:191] op_sel_hi:[1,0]
	v_pk_mul_f32 v[12:13], v[12:13], v[4:5]
	v_pk_mul_f32 v[14:15], v[14:15], v[6:7]
	v_pk_mul_f32 v[8:9], v[8:9], v[0:1]
	v_pk_mul_f32 v[10:11], v[10:11], v[2:3]
	s_cmp_eq_u32 s7, 1
	s_cbranch_scc1 .Lme_f32_7
	s_cmp_eq_u32 s7, 2
	s_cbranch_scc0 .Lme_nof32_7
.Lme_f32_7:
	s_mov_b64 s[12:13], exec
	s_and_b64 exec, exec, s[18:19]
	global_store_dwordx4 v216, v[12:15], s[8:9]
	global_store_dwordx4 v216, v[8:11], s[8:9] offset:16
	s_mov_b64 exec, s[12:13]
.Lme_nof32_7:
	v_cvt_pk_bf16_f32 v108, v12, v13
	v_cvt_pk_bf16_f32 v109, v14, v15
	v_cvt_pk_bf16_f32 v110, v8, v9
	v_cvt_pk_bf16_f32 v111, v10, v11
	global_store_dwordx4 v214, v[108:111], s[16:17]
	s_branch .LBB0_580

; template <class T, class P> __device__ __forceinline__ T gld_nt(P p) { return __builtin_nontemporal_load((GAS const T*)p); }
; __device__ __forceinline__ u32x2 pk4(f32x4 a) { u32x2 w; w.x = pk2(a[0], a[1]); w.y = pk2(a[2], a[3]); return w; }
; __device__ __forceinline__ void p0_phase(LAS unsigned char* lds, const Args& a, const int w0) {
;     ...
;     for (int i = gt; i < DEPTH * MR * 64; i += 4 * GT) {
;         f32x4 v[4];
; #pragma unroll
;         for (int j = 0; j < 4; ++j) { const int ii = i + j * GT; const int ic = ii < DEPTH * MR * 64 ? ii : i; const int L = ic / (MR * 64), q = ic % (MR * 64), row = q >> 6, c4 = q & 63;
;             const float* src = row < NPR ? a.in[5] + ((size_t)L * NPR + row) * PLE : a.in[6] + ((size_t)L * NSR + row - NPR) * PLE; v[j] = gld_nt<f32x4>(src + c4 * 4); }
; #pragma unroll
;         for (int j = 0; j < 4; ++j) { const int ii = i + j * GT; if (ii < DEPTH * MR * 64) *(u32x2*)((bf16_t*)(ws + WS_PB) + (size_t)ii * 4) = pk4(v[j]); }
.LBB0_647:
	s_or_b64 exec, exec, s[4:5]
	s_cmp_lt_u32 s40, 64
	s_cbranch_scc1 .Ldp_a_skip
	v_readlane_b32 s14, v255, 36
	s_load_dwordx4 s[8:11], s[0:1], 0x28
	s_load_dwordx2 s[12:13], s[0:1], 0x80
	s_cmp_gt_u32 s14, 2
	s_cbranch_scc1 .Ldp_a_skip0
	s_add_i32 s14, s14, 1
	s_mov_b64 s[26:27], exec
	s_mul_i32 s16, s46, 0x1c0
	s_add_i32 s16, s16, s40
	s_add_i32 s16, s16, 0xffffffc0
	v_mbcnt_lo_u32_b32 v0, -1, 0
	v_mbcnt_hi_u32_b32 v0, -1, v0
	s_mul_i32 s17, s24, 0x1c0
	s_mov_b32 s18, 0x100000
	v_add_u32_e32 v0, s16, v0
	s_mul_i32 s19, s17, 4
	s_waitcnt lgkmcnt(0)
	s_lshl_b32 s15, s14, 24
	s_add_u32 s8, s8, s15
	s_addc_u32 s9, s9, 0
	s_lshl_b32 s15, s14, 19
	s_add_u32 s10, s10, s15
	s_addc_u32 s11, s11, 0
	s_mul_i32 s15, s14, 0x840000
	s_add_u32 s12, s12, s15
	s_addc_u32 s13, s13, 0
	s_add_u32 s12, s12, 0x4f00000
	s_addc_u32 s13, s13, 0
